# speedup vs baseline: 1.0881x; 1.0305x over previous
; DEV void rowwise_row(int row, int lane, const bf16_t* __restrict__ add, const float* __restrict__ gpost, const float* __restrict__ xin,
;                      float* __restrict__ xout, const float* __restrict__ gpre, bf16_t* __restrict__ hin, float* __restrict__ fout) {
;     ...
;   if (gpre) {
;     float ss = 0.f;
; #pragma unroll
;     for (int j = 0; j < 8; ++j) ss += xv[j].x * xv[j].x + xv[j].y * xv[j].y + xv[j].z * xv[j].z + xv[j].w * xv[j].w;
;     ss = wave_sum(ss);
;     float rs = rsqrtf(ss * (1.f / DM) + EPS);
; #pragma unroll
;     for (int j = 0; j < 8; ++j) {
;       float4 g = *(const float4*)(gpre + j * 256 + lane * 4);
;       uint2 o; o.x = cvtpk(xv[j].x * rs * g.x, xv[j].y * rs * g.y); o.y = cvtpk(xv[j].z * rs * g.z, xv[j].w * rs * g.w);
;       *(uint2*)(hin + base + j * 256 + lane * 4) = o;
;     }
.LBB0_52:
	s_andn2_b64 vcc, exec, s[8:9]
	s_cbranch_vccnz .LBB0_48
	v_pk_mul_f32 v[62:63], v[30:31], v[30:31]
	v_pk_mul_f32 v[72:73], v[26:27], v[26:27]
	v_pk_mul_f32 v[70:71], v[32:33], v[32:33]
	v_pk_mul_f32 v[74:75], v[28:29], v[28:29]
	v_add_f32_e32 v35, v72, v73
	v_add_f32_e32 v62, v62, v63
	v_add_f32_e32 v35, v74, v35
	v_add_f32_e32 v62, v70, v62
	v_pk_mul_f32 v[76:77], v[22:23], v[22:23]
	v_add_f32_e32 v35, v75, v35
	v_add_f32_e32 v62, v71, v62
	v_pk_mul_f32 v[78:79], v[24:25], v[24:25]
	v_add_f32_e32 v35, v62, v35
	v_add_f32_e32 v62, v76, v77
	v_mov_b32_e32 v86, v15
	v_mov_b32_e32 v87, v11
	v_add_f32_e32 v62, v78, v62
	v_pk_mul_f32 v[80:81], v[18:19], v[18:19]
	v_mov_b32_e32 v84, v14
	v_mov_b32_e32 v85, v10
	v_pk_mul_f32 v[86:87], v[86:87], v[86:87]
	v_add_f32_e32 v62, v79, v62
	v_pk_mul_f32 v[82:83], v[20:21], v[20:21]
	v_pk_fma_f32 v[84:85], v[84:85], v[84:85], v[86:87]
	v_mov_b32_e32 v86, v16
	v_mov_b32_e32 v87, v12
	v_add_f32_e32 v35, v62, v35
	v_add_f32_e32 v62, v80, v81
	v_pk_fma_f32 v[84:85], v[86:87], v[86:87], v[84:85]
	v_mov_b32_e32 v86, v17
	v_mov_b32_e32 v87, v13
	v_mov_b32_e32 v88, v7
	v_mov_b32_e32 v89, v3
	v_add_f32_e32 v62, v62, v82
	v_pk_fma_f32 v[84:85], v[86:87], v[86:87], v[84:85]
	v_mov_b32_e32 v86, v6
	v_mov_b32_e32 v87, v2
	v_pk_mul_f32 v[88:89], v[88:89], v[88:89]
	v_add_f32_e32 v62, v62, v83
	v_pk_fma_f32 v[86:87], v[86:87], v[86:87], v[88:89]
	v_mov_b32_e32 v88, v8
	v_mov_b32_e32 v89, v4
	v_add_f32_e32 v35, v35, v62
	v_pk_fma_f32 v[86:87], v[88:89], v[88:89], v[86:87]
	v_mov_b32_e32 v88, v9
	v_mov_b32_e32 v89, v5
	v_add_f32_e32 v35, v35, v84
	v_pk_fma_f32 v[86:87], v[88:89], v[88:89], v[86:87]
	v_add_f32_e32 v35, v35, v85
	v_add_f32_e32 v35, v35, v86
	v_add_f32_e32 v35, v35, v87
	ds_bpermute_b32 v1, v1, v35
	v_lshl_add_u64 v[62:63], v[66:67], 1, s[10:11]
	s_mov_b64 s[6:7], 0x1d6e0000
	s_waitcnt lgkmcnt(0)
	v_add_f32_e32 v1, v35, v1
	ds_bpermute_b32 v35, v61, v1
	v_mov_b32_e32 v61, v0
	v_lshl_add_u64 v[70:71], v[62:63], 0, v[60:61]
	v_lshl_add_u64 v[62:63], v[70:71], 0, s[6:7]
	s_mov_b32 s6, 0x1d6e0000
	s_waitcnt lgkmcnt(0)
	v_add_f32_e32 v1, v1, v35
	ds_bpermute_b32 v35, v64, v1
	s_waitcnt lgkmcnt(0)
	v_add_f32_e32 v1, v1, v35
	ds_bpermute_b32 v35, v65, v1
	s_waitcnt lgkmcnt(0)
	v_add_f32_e32 v1, v1, v35
	ds_bpermute_b32 v35, v68, v1
	s_waitcnt lgkmcnt(0)
	v_add_f32_e32 v1, v1, v35
	ds_bpermute_b32 v35, v69, v1
	global_load_dwordx4 v[66:69], v[50:51], off
	global_load_dwordx4 v[178:181], v[50:51], off offset:1024
	global_load_dwordx4 v[182:185], v[50:51], off offset:2048
	global_load_dwordx4 v[186:189], v[50:51], off offset:3072
	global_load_dwordx4 v[214:217], v[52:53], off
	global_load_dwordx4 v[218:221], v[54:55], off
	global_load_dwordx4 v[222:225], v[56:57], off
	global_load_dwordx4 v[226:229], v[58:59], off
	s_waitcnt lgkmcnt(0)
	v_add_f32_e32 v1, v1, v35
	v_fmamk_f32 v1, v1, 0x3a000000, v195
	v_cmp_gt_f32_e32 vcc, s38, v1
	v_mul_f32_e32 v35, 0x4b800000, v1
	s_nop 0
	v_cndmask_b32_e32 v1, v1, v35, vcc
	v_rsq_f32_e32 v1, v1
	s_nop 0
	v_mul_f32_e32 v35, 0x45800000, v1
	v_cndmask_b32_e32 v64, v1, v35, vcc
	v_pk_mul_f32 v[30:31], v[30:31], v[64:65] op_sel_hi:[1,0]
	v_pk_mul_f32 v[32:33], v[32:33], v[64:65] op_sel_hi:[1,0]
	v_pk_mul_f32 v[26:27], v[26:27], v[64:65] op_sel_hi:[1,0]
	v_pk_mul_f32 v[28:29], v[28:29], v[64:65] op_sel_hi:[1,0]
	v_pk_mul_f32 v[22:23], v[22:23], v[64:65] op_sel_hi:[1,0]
	v_pk_mul_f32 v[24:25], v[24:25], v[64:65] op_sel_hi:[1,0]
	v_pk_mul_f32 v[18:19], v[18:19], v[64:65] op_sel_hi:[1,0]
	v_pk_mul_f32 v[20:21], v[20:21], v[64:65] op_sel_hi:[1,0]
	v_pk_mul_f32 v[14:15], v[14:15], v[64:65] op_sel_hi:[1,0]
	v_pk_mul_f32 v[16:17], v[16:17], v[64:65] op_sel_hi:[1,0]
	v_pk_mul_f32 v[10:11], v[10:11], v[64:65] op_sel_hi:[1,0]
	v_pk_mul_f32 v[12:13], v[12:13], v[64:65] op_sel_hi:[1,0]
	v_pk_mul_f32 v[6:7], v[6:7], v[64:65] op_sel_hi:[1,0]
	v_pk_mul_f32 v[8:9], v[8:9], v[64:65] op_sel_hi:[1,0]
	v_pk_mul_f32 v[2:3], v[2:3], v[64:65] op_sel_hi:[1,0]
	v_pk_mul_f32 v[4:5], v[4:5], v[64:65] op_sel_hi:[1,0]
	s_waitcnt vmcnt(0)
	v_pk_mul_f32 v[30:31], v[66:67], v[30:31]
	v_pk_mul_f32 v[32:33], v[68:69], v[32:33]
	v_cvt_pk_bf16_f32 v30, v30, v31
	v_cvt_pk_bf16_f32 v31, v32, v33
	v_add_co_u32_e32 v32, vcc, s6, v70
	s_nop 1
	v_addc_co_u32_e32 v33, vcc, 0, v71, vcc
	flat_store_dwordx2 v[32:33], v[30:31]
	v_mov_b32_e32 v30, v178
	v_mov_b32_e32 v31, v179
	v_mov_b32_e32 v32, v180
	v_mov_b32_e32 v33, v181
	s_nop 0
	v_pk_mul_f32 v[26:27], v[30:31], v[26:27]
	v_pk_mul_f32 v[28:29], v[32:33], v[28:29]
	v_cvt_pk_bf16_f32 v26, v26, v27
	v_cvt_pk_bf16_f32 v27, v28, v29
	flat_store_dwordx2 v[62:63], v[26:27] offset:512
	v_mov_b32_e32 v26, v182
	v_mov_b32_e32 v27, v183
	v_mov_b32_e32 v28, v184
	v_mov_b32_e32 v29, v185
	s_nop 0
	v_pk_mul_f32 v[22:23], v[22:23], v[26:27]
	v_pk_mul_f32 v[24:25], v[24:25], v[28:29]
	v_cvt_pk_bf16_f32 v22, v22, v23
	v_cvt_pk_bf16_f32 v23, v24, v25
	flat_store_dwordx2 v[62:63], v[22:23] offset:1024
	v_mov_b32_e32 v22, v186
	v_mov_b32_e32 v23, v187
	v_mov_b32_e32 v24, v188
	v_mov_b32_e32 v25, v189
	s_nop 0
	v_pk_mul_f32 v[18:19], v[18:19], v[22:23]
	v_pk_mul_f32 v[20:21], v[20:21], v[24:25]
	v_cvt_pk_bf16_f32 v18, v18, v19
	v_cvt_pk_bf16_f32 v19, v20, v21
	flat_store_dwordx2 v[62:63], v[18:19] offset:1536
	v_mov_b32_e32 v18, v214
	v_mov_b32_e32 v19, v215
	v_mov_b32_e32 v20, v216
	v_mov_b32_e32 v21, v217
	s_nop 0
	v_pk_mul_f32 v[14:15], v[14:15], v[18:19]
	v_pk_mul_f32 v[16:17], v[16:17], v[20:21]
	v_cvt_pk_bf16_f32 v14, v14, v15
	v_cvt_pk_bf16_f32 v15, v16, v17
	flat_store_dwordx2 v[62:63], v[14:15] offset:2048
	v_mov_b32_e32 v14, v218
	v_mov_b32_e32 v15, v219
	v_mov_b32_e32 v16, v220
	v_mov_b32_e32 v17, v221
	s_nop 0
	v_pk_mul_f32 v[10:11], v[10:11], v[14:15]
	v_pk_mul_f32 v[12:13], v[12:13], v[16:17]
	v_cvt_pk_bf16_f32 v10, v10, v11
	v_cvt_pk_bf16_f32 v11, v12, v13
	flat_store_dwordx2 v[62:63], v[10:11] offset:2560
	v_mov_b32_e32 v10, v222
	v_mov_b32_e32 v11, v223
	v_mov_b32_e32 v12, v224
	v_mov_b32_e32 v13, v225
	s_nop 0
	v_pk_mul_f32 v[6:7], v[6:7], v[10:11]
	v_pk_mul_f32 v[8:9], v[8:9], v[12:13]
	v_cvt_pk_bf16_f32 v6, v6, v7
	v_cvt_pk_bf16_f32 v7, v8, v9
	flat_store_dwordx2 v[62:63], v[6:7] offset:3072
	v_mov_b32_e32 v6, v226
	v_mov_b32_e32 v7, v227
	v_mov_b32_e32 v8, v228
	v_mov_b32_e32 v9, v229
	s_nop 0
	v_pk_mul_f32 v[2:3], v[2:3], v[6:7]
	v_pk_mul_f32 v[4:5], v[4:5], v[8:9]
	v_cvt_pk_bf16_f32 v2, v2, v3
	v_cvt_pk_bf16_f32 v3, v4, v5
	flat_store_dwordx2 v[62:63], v[2:3] offset:3584
	s_branch .LBB0_48

; DEV f32x16 mfma(bf16x8 a, bf16x8 b, f32x16 c) { return __builtin_amdgcn_mfma_f32_32x32x16_bf16(a, b, c, 0, 0, 0); }
;     ...
;   for (int kt = 0; kt < nk; ++kt) {
;     if (kt + 1 < nk) { if (MI == 4) asm volatile("s_waitcnt vmcnt(6)" ::: "memory"); else asm volatile("s_waitcnt vmcnt(4)" ::: "memory"); } else asm volatile("s_waitcnt vmcnt(0)" ::: "memory");
;     __builtin_amdgcn_s_barrier();
;     if (kt + 2 < nk) { int s2 = stg + 2; if (s2 >= 3) s2 -= 3; g2_issue<MI>(ag + (size_t)(kt + 2) * 32, bg + (size_t)(kt + 2) * 32, lda, ldb, voffa, voffb, lds + s2 * G2_STAGE, w); }
;     const unsigned so = (unsigned)(stg * G2_STAGE);
;     __builtin_amdgcn_s_setprio(1);
; #pragma unroll
;     for (int ks = 0; ks < 2; ++ks) {
;       const unsigned aa = (ks ? la1 : la0) + so, bb = (ks ? lb1 : lb0) + so;
;       bf16x8 fb0, fb1, fa0, fa1, fa2, fa3;
;       asm volatile("ds_read_b128 %0, %1" : "=v"(fb0) : "v"(bb));
;       asm volatile("ds_read_b128 %0, %1 offset:2048" : "=v"(fb1) : "v"(bb));
;       asm volatile("ds_read_b128 %0, %1" : "=v"(fa0) : "v"(aa));
;       asm volatile("ds_read_b128 %0, %1 offset:2048" : "=v"(fa1) : "v"(aa));
;       if constexpr (MI == 4) {
;         asm volatile("ds_read_b128 %0, %1 offset:4096" : "=v"(fa2) : "v"(aa));
;         asm volatile("ds_read_b128 %0, %1 offset:6144" : "=v"(fa3) : "v"(aa));
;         __builtin_amdgcn_sched_barrier(0);
;         asm volatile("s_waitcnt lgkmcnt(3)" : "+v"(fb0), "+v"(fb1), "+v"(fa0));
;         acc[0][0][0] = mfma(fa0, fb0, acc[0][0][0]); acc[0][0][1] = mfma(fa0, fb1, acc[0][0][1]); __builtin_amdgcn_sched_barrier(0);
;         asm volatile("s_waitcnt lgkmcnt(2)" : "+v"(fa1));
;         acc[0][1][0] = mfma(fa1, fb0, acc[0][1][0]); acc[0][1][1] = mfma(fa1, fb1, acc[0][1][1]); __builtin_amdgcn_sched_barrier(0);
;         asm volatile("s_waitcnt lgkmcnt(1)" : "+v"(fa2));
;         acc[MI / 2 - 1][0][0] = mfma(fa2, fb0, acc[MI / 2 - 1][0][0]); acc[MI / 2 - 1][0][1] = mfma(fa2, fb1, acc[MI / 2 - 1][0][1]); __builtin_amdgcn_sched_barrier(0);
;         asm volatile("s_waitcnt lgkmcnt(0)" : "+v"(fa3));
;         acc[MI / 2 - 1][1][0] = mfma(fa3, fb0, acc[MI / 2 - 1][1][0]); acc[MI / 2 - 1][1][1] = mfma(fa3, fb1, acc[MI / 2 - 1][1][1]); __builtin_amdgcn_sched_barrier(0);
;       } else {
;         __builtin_amdgcn_sched_barrier(0);
;         asm volatile("s_waitcnt lgkmcnt(1)" : "+v"(fb0), "+v"(fb1), "+v"(fa0));
.Lhy2_issue_down:
	s_mul_i32 s99, s6, 0x6000
	s_setprio 1
	v_add_u32_e32 v147, s99, v141
	v_add_u32_e32 v149, s99, v143
	v_add_u32_e32 v172, v147, v145
	v_add_u32_e32 v156, v149, v145
	ds_read_b128 v[152:155], v156
	ds_read_b128 v[156:159], v156 offset:2048
	ds_read_b128 v[160:163], v172
	ds_read_b128 v[164:167], v172 offset:2048
	ds_read_b128 v[168:171], v172 offset:4096
	ds_read_b128 v[172:175], v172 offset:6144
	s_cmpk_eq_i32 s18, 0x2b80
	s_cbranch_scc1 .Lhy2_noissue_down
	s_nop 0
	s_waitcnt lgkmcnt(3)
	s_nop 0
	v_mfma_f32_32x32x16_bf16 v[114:129], v[160:163], v[152:155], v[114:129]
	v_mfma_f32_32x32x16_bf16 v[98:113], v[160:163], v[156:159], v[98:113]
	s_mov_b32 m0, s84
	s_nop 0
	global_load_lds_dwordx4 v1, s[82:83]
	global_load_dwordx4 v[214:217], v1, s[82:83] offset:64
	s_add_u32 s82, s78, s18
	s_addc_u32 s83, s79, s19
	s_add_i32 s84, s58, s81
	s_mov_b32 m0, s84
	s_nop 0
	global_load_lds_dwordx4 v1, s[82:83]
	global_load_dwordx4 v[218:221], v1, s[82:83] offset:64
	s_waitcnt lgkmcnt(2)
	s_nop 0
	v_mfma_f32_32x32x16_bf16 v[82:97], v[164:167], v[152:155], v[82:97]
	v_mfma_f32_32x32x16_bf16 v[66:81], v[164:167], v[156:159], v[66:81]
	s_add_u32 s82, s76, s18
	s_addc_u32 s83, s77, s19
	s_add_i32 s84, s57, s81
	s_mov_b32 m0, s84
	s_nop 0
	global_load_lds_dwordx4 v1, s[82:83]
	global_load_dwordx4 v[222:225], v1, s[82:83] offset:64
	s_add_u32 s82, s74, s18
	s_addc_u32 s83, s75, s19
	s_add_i32 s84, s56, s81
	s_addk_i32 s81, 0x4000
	s_mov_b32 m0, s84
	s_nop 0
	global_load_lds_dwordx4 v1, s[82:83]
	global_load_dwordx4 v[226:229], v1, s[82:83] offset:64
	s_waitcnt lgkmcnt(1)
	s_nop 0
	v_mfma_f32_32x32x16_bf16 v[50:65], v[168:171], v[152:155], v[50:65]
	v_mfma_f32_32x32x16_bf16 v[34:49], v[168:171], v[156:159], v[34:49]
	s_add_u32 s82, s63, s18
	s_addc_u32 s83, s64, s19
	s_add_i32 s84, s81, s55
	s_mov_b32 m0, s84
	s_nop 0
	global_load_lds_dwordx4 v1, s[82:83]
	global_load_dwordx4 v[230:233], v1, s[82:83] offset:64
	s_add_u32 s82, s60, s18
	s_addc_u32 s83, s61, s19
	s_add_i32 s81, s81, s54
	s_mov_b32 m0, s81
	s_nop 0
	global_load_lds_dwordx4 v1, s[82:83]
	global_load_dwordx4 v[234:237], v1, s[82:83] offset:64
	s_waitcnt lgkmcnt(0)
	s_nop 0
	v_mfma_f32_32x32x16_bf16 v[18:33], v[172:175], v[152:155], v[18:33]
	v_mfma_f32_32x32x16_bf16 v[2:17], v[172:175], v[156:159], v[2:17]
	s_branch .Lhy2_after_down
.Lhy2_noissue_down:
	s_nop 0
	s_waitcnt lgkmcnt(3)
	s_nop 0
	v_mfma_f32_32x32x16_bf16 v[114:129], v[160:163], v[152:155], v[114:129]
	v_mfma_f32_32x32x16_bf16 v[98:113], v[160:163], v[156:159], v[98:113]
	s_waitcnt lgkmcnt(2)
	s_nop 0
	v_mfma_f32_32x32x16_bf16 v[82:97], v[164:167], v[152:155], v[82:97]
	v_mfma_f32_32x32x16_bf16 v[66:81], v[164:167], v[156:159], v[66:81]
	s_waitcnt lgkmcnt(1)
	s_nop 0
	v_mfma_f32_32x32x16_bf16 v[50:65], v[168:171], v[152:155], v[50:65]
	v_mfma_f32_32x32x16_bf16 v[34:49], v[168:171], v[156:159], v[34:49]
	s_waitcnt lgkmcnt(0)
	s_nop 0
	v_mfma_f32_32x32x16_bf16 v[18:33], v[172:175], v[152:155], v[18:33]
	v_mfma_f32_32x32x16_bf16 v[2:17], v[172:175], v[156:159], v[2:17]
; DEV f32x16 mfma(bf16x8 a, bf16x8 b, f32x16 c) { return __builtin_amdgcn_mfma_f32_32x32x16_bf16(a, b, c, 0, 0, 0); }
;     ...
;   for (int kt = 0; kt < nk; ++kt) {
;     if (kt + 1 < nk) { if (MI == 4) asm volatile("s_waitcnt vmcnt(6)" ::: "memory"); else asm volatile("s_waitcnt vmcnt(4)" ::: "memory"); } else asm volatile("s_waitcnt vmcnt(0)" ::: "memory");
;     __builtin_amdgcn_s_barrier();
;     if (kt + 2 < nk) { int s2 = stg + 2; if (s2 >= 3) s2 -= 3; g2_issue<MI>(ag + (size_t)(kt + 2) * 32, bg + (size_t)(kt + 2) * 32, lda, ldb, voffa, voffb, lds + s2 * G2_STAGE, w); }
;     const unsigned so = (unsigned)(stg * G2_STAGE);
;     __builtin_amdgcn_s_setprio(1);
; #pragma unroll
;     for (int ks = 0; ks < 2; ++ks) {
;       const unsigned aa = (ks ? la1 : la0) + so, bb = (ks ? lb1 : lb0) + so;
;       bf16x8 fb0, fb1, fa0, fa1, fa2, fa3;
;       asm volatile("ds_read_b128 %0, %1" : "=v"(fb0) : "v"(bb));
;       asm volatile("ds_read_b128 %0, %1 offset:2048" : "=v"(fb1) : "v"(bb));
;       asm volatile("ds_read_b128 %0, %1" : "=v"(fa0) : "v"(aa));
;       asm volatile("ds_read_b128 %0, %1 offset:2048" : "=v"(fa1) : "v"(aa));
;       if constexpr (MI == 4) {
;         asm volatile("ds_read_b128 %0, %1 offset:4096" : "=v"(fa2) : "v"(aa));
;         asm volatile("ds_read_b128 %0, %1 offset:6144" : "=v"(fa3) : "v"(aa));
;         __builtin_amdgcn_sched_barrier(0);
;         asm volatile("s_waitcnt lgkmcnt(3)" : "+v"(fb0), "+v"(fb1), "+v"(fa0));
;         acc[0][0][0] = mfma(fa0, fb0, acc[0][0][0]); acc[0][0][1] = mfma(fa0, fb1, acc[0][0][1]); __builtin_amdgcn_sched_barrier(0);
;         asm volatile("s_waitcnt lgkmcnt(2)" : "+v"(fa1));
;         acc[0][1][0] = mfma(fa1, fb0, acc[0][1][0]); acc[0][1][1] = mfma(fa1, fb1, acc[0][1][1]); __builtin_amdgcn_sched_barrier(0);
;         asm volatile("s_waitcnt lgkmcnt(1)" : "+v"(fa2));
;         acc[MI / 2 - 1][0][0] = mfma(fa2, fb0, acc[MI / 2 - 1][0][0]); acc[MI / 2 - 1][0][1] = mfma(fa2, fb1, acc[MI / 2 - 1][0][1]); __builtin_amdgcn_sched_barrier(0);
;         asm volatile("s_waitcnt lgkmcnt(0)" : "+v"(fa3));
;         acc[MI / 2 - 1][1][0] = mfma(fa3, fb0, acc[MI / 2 - 1][1][0]); acc[MI / 2 - 1][1][1] = mfma(fa3, fb1, acc[MI / 2 - 1][1][1]); __builtin_amdgcn_sched_barrier(0);
;       } else {
;         __builtin_amdgcn_sched_barrier(0);
;         asm volatile("s_waitcnt lgkmcnt(1)" : "+v"(fb0), "+v"(fb1), "+v"(fa0));
.Lhy2_after_down:
	v_add_u32_e32 v147, v147, v138
	v_add_u32_e32 v149, v149, v138
	ds_read_b128 v[152:155], v149
	ds_read_b128 v[156:159], v149 offset:2048
	ds_read_b128 v[160:163], v147
	ds_read_b128 v[164:167], v147 offset:2048
	ds_read_b128 v[168:171], v147 offset:4096
	ds_read_b128 v[172:175], v147 offset:6144
	s_nop 0
	s_waitcnt lgkmcnt(3)
	s_nop 0
	v_mfma_f32_32x32x16_bf16 v[114:129], v[160:163], v[152:155], v[114:129]
	v_mfma_f32_32x32x16_bf16 v[98:113], v[160:163], v[156:159], v[98:113]
	s_waitcnt lgkmcnt(2)
	s_nop 0
	v_mfma_f32_32x32x16_bf16 v[82:97], v[164:167], v[152:155], v[82:97]
	v_mfma_f32_32x32x16_bf16 v[66:81], v[164:167], v[156:159], v[66:81]
	s_waitcnt lgkmcnt(1)
	s_nop 0
	v_mfma_f32_32x32x16_bf16 v[50:65], v[168:171], v[152:155], v[50:65]
	v_mfma_f32_32x32x16_bf16 v[34:49], v[168:171], v[156:159], v[34:49]
	s_waitcnt lgkmcnt(0)
	s_nop 0
	v_mfma_f32_32x32x16_bf16 v[18:33], v[172:175], v[152:155], v[18:33]
	v_mfma_f32_32x32x16_bf16 v[2:17], v[172:175], v[156:159], v[2:17]
	s_setprio 0
	s_add_i32 s98, s6, 1
	s_cmp_lg_u32 s6, 2
	s_cselect_b32 s6, s98, 0
	s_waitcnt vmcnt(12)
	s_barrier
	s_mul_i32 s81, s6, 0x6000
	s_setprio 1
	v_add_u32_e32 v147, s81, v141
	v_add_u32_e32 v149, s81, v143
	v_add_u32_e32 v172, v147, v145
	v_add_u32_e32 v156, v149, v145
	ds_read_b128 v[152:155], v156
	ds_read_b128 v[156:159], v156 offset:2048
	ds_read_b128 v[160:163], v172
	ds_read_b128 v[164:167], v172 offset:2048
	ds_read_b128 v[168:171], v172 offset:4096
	ds_read_b128 v[172:175], v172 offset:6144
	s_nop 0
	s_waitcnt lgkmcnt(3)
	s_nop 0
	v_mfma_f32_32x32x16_bf16 v[114:129], v[160:163], v[152:155], v[114:129]
	v_mfma_f32_32x32x16_bf16 v[98:113], v[160:163], v[156:159], v[98:113]
	s_waitcnt lgkmcnt(2)
	s_nop 0
	v_mfma_f32_32x32x16_bf16 v[82:97], v[164:167], v[152:155], v[82:97]
	v_mfma_f32_32x32x16_bf16 v[66:81], v[164:167], v[156:159], v[66:81]
	s_waitcnt lgkmcnt(1)
	s_nop 0
	v_mfma_f32_32x32x16_bf16 v[50:65], v[168:171], v[152:155], v[50:65]
	v_mfma_f32_32x32x16_bf16 v[34:49], v[168:171], v[156:159], v[34:49]
	s_waitcnt lgkmcnt(0)
	s_nop 0
	v_mfma_f32_32x32x16_bf16 v[18:33], v[172:175], v[152:155], v[18:33]
	v_mfma_f32_32x32x16_bf16 v[2:17], v[172:175], v[156:159], v[2:17]
	v_add_u32_e32 v147, v147, v138
	v_add_u32_e32 v149, v149, v138
	ds_read_b128 v[152:155], v149
	ds_read_b128 v[156:159], v149 offset:2048
	ds_read_b128 v[160:163], v147
	ds_read_b128 v[164:167], v147 offset:2048
	ds_read_b128 v[168:171], v147 offset:4096
	ds_read_b128 v[172:175], v147 offset:6144
	s_nop 0
	s_waitcnt lgkmcnt(3)
	s_nop 0
	v_mfma_f32_32x32x16_bf16 v[114:129], v[160:163], v[152:155], v[114:129]
	v_mfma_f32_32x32x16_bf16 v[98:113], v[160:163], v[156:159], v[98:113]
	s_waitcnt lgkmcnt(2)
	s_nop 0
	v_mfma_f32_32x32x16_bf16 v[82:97], v[164:167], v[152:155], v[82:97]
	v_mfma_f32_32x32x16_bf16 v[66:81], v[164:167], v[156:159], v[66:81]
	s_waitcnt lgkmcnt(1)
	s_nop 0
	v_mfma_f32_32x32x16_bf16 v[50:65], v[168:171], v[152:155], v[50:65]
	v_mfma_f32_32x32x16_bf16 v[34:49], v[168:171], v[156:159], v[34:49]
	s_waitcnt lgkmcnt(0)
	s_nop 0
	v_mfma_f32_32x32x16_bf16 v[18:33], v[172:175], v[152:155], v[18:33]
	v_mfma_f32_32x32x16_bf16 v[2:17], v[172:175], v[156:159], v[2:17]
	s_add_i32 s98, s6, 1
	s_cmp_lg_u32 s6, 2
	s_cselect_b32 s6, s98, 0
	s_add_u32 s18, s18, 0x80
	s_addc_u32 s19, s19, 0
	s_cmpk_eq_i32 s18, 0x2c00
	s_cbranch_scc0 .LBB0_79
	s_setprio 0
	s_and_b64 vcc, exec, s[2:3]
	s_waitcnt lgkmcnt(0)
	s_barrier
	s_cbranch_vccz .LBB0_67
	s_lshl_b32 s2, s21, 8
	s_lshl_b32 s3, s22, 7
	s_mul_i32 s6, s21, 0x2c0000
	s_mul_hi_i32 s2, s2, 0x2c00
	s_add_u32 s18, s23, s6
	s_addc_u32 s19, s24, s2
	s_mul_i32 s2, s22, 0x160000
	s_mul_hi_i32 s3, s3, 0x2c00
	s_add_u32 s60, s25, s2
	s_addc_u32 s61, s26, s3
	s_add_u32 s2, s18, s16
	s_addc_u32 s3, s19, s17
	s_add_u32 s6, s18, s14
	s_addc_u32 s7, s19, s15
	s_add_u32 s12, s18, s12
	s_addc_u32 s13, s19, s13
	s_add_u32 s10, s18, s10
	s_mov_b32 m0, s59
	s_nop 0
	global_load_lds_dwordx4 v1, s[2:3]
	s_addc_u32 s11, s19, s11
	s_mov_b32 m0, s58
	s_nop 0
	global_load_lds_dwordx4 v1, s[6:7]
	s_add_u32 s8, s60, s8
	s_mov_b32 m0, s57
	s_nop 0
	global_load_lds_dwordx4 v1, s[12:13]
	s_addc_u32 s9, s61, s9
	s_add_i32 s14, s55, 0x4000
	s_mov_b32 m0, s56
	s_nop 0
	global_load_lds_dwordx4 v1, s[10:11]
	s_add_u32 s4, s60, s4
	s_mov_b32 m0, s14
	s_nop 0
	global_load_lds_dwordx4 v1, s[8:9]
	s_addc_u32 s5, s61, s5
	s_add_i32 s14, s54, 0x4000
	s_add_u32 s2, s2, 64
	s_mov_b32 m0, s14
	s_nop 0
	global_load_lds_dwordx4 v1, s[4:5]
	s_addc_u32 s3, s3, 0
	s_add_i32 s14, s59, 0x6000
	s_mov_b32 m0, s14
	s_nop 0
	global_load_lds_dwordx4 v1, s[2:3]
	s_add_u32 s2, s6, 64
	s_addc_u32 s3, s7, 0
	s_add_i32 s6, s58, 0x6000
	s_mov_b32 m0, s6
	s_nop 0
	global_load_lds_dwordx4 v1, s[2:3]
	s_add_u32 s2, s12, 64
	s_addc_u32 s3, s13, 0
	s_add_i32 s6, s57, 0x6000
	s_mov_b32 m0, s6
	s_nop 0
	global_load_lds_dwordx4 v1, s[2:3]
	s_add_u32 s2, s10, 64
	s_addc_u32 s3, s11, 0
	s_add_i32 s6, s56, 0x6000
	s_mov_b32 m0, s6
	s_nop 0
	global_load_lds_dwordx4 v1, s[2:3]
	s_add_u32 s2, s8, 64
	s_addc_u32 s3, s9, 0
	s_add_i32 s55, s55, 0xa000
	s_mov_b32 m0, s55
	s_nop 0
	global_load_lds_dwordx4 v1, s[2:3]
	s_add_u32 s2, s4, 64
	s_addc_u32 s3, s5, 0
	s_add_i32 s54, s54, 0xa000
	s_mov_b32 m0, s54
	s_nop 0
	global_load_lds_dwordx4 v1, s[2:3]
	s_branch .LBB0_67

; DEV f32x16 mfma(bf16x8 a, bf16x8 b, f32x16 c) { return __builtin_amdgcn_mfma_f32_32x32x16_bf16(a, b, c, 0, 0, 0); }
;     ...
;   for (int kt = 0; kt < nk; ++kt) {
;     if (kt + 1 < nk) { if (MI == 4) asm volatile("s_waitcnt vmcnt(6)" ::: "memory"); else asm volatile("s_waitcnt vmcnt(4)" ::: "memory"); } else asm volatile("s_waitcnt vmcnt(0)" ::: "memory");
;     __builtin_amdgcn_s_barrier();
;     if (kt + 2 < nk) { int s2 = stg + 2; if (s2 >= 3) s2 -= 3; g2_issue<MI>(ag + (size_t)(kt + 2) * 32, bg + (size_t)(kt + 2) * 32, lda, ldb, voffa, voffb, lds + s2 * G2_STAGE, w); }
;     const unsigned so = (unsigned)(stg * G2_STAGE);
;     __builtin_amdgcn_s_setprio(1);
; #pragma unroll
;     for (int ks = 0; ks < 2; ++ks) {
;       const unsigned aa = (ks ? la1 : la0) + so, bb = (ks ? lb1 : lb0) + so;
;       bf16x8 fb0, fb1, fa0, fa1, fa2, fa3;
;       asm volatile("ds_read_b128 %0, %1" : "=v"(fb0) : "v"(bb));
;       asm volatile("ds_read_b128 %0, %1 offset:2048" : "=v"(fb1) : "v"(bb));
;       asm volatile("ds_read_b128 %0, %1" : "=v"(fa0) : "v"(aa));
;       asm volatile("ds_read_b128 %0, %1 offset:2048" : "=v"(fa1) : "v"(aa));
;       if constexpr (MI == 4) {
;         asm volatile("ds_read_b128 %0, %1 offset:4096" : "=v"(fa2) : "v"(aa));
;         asm volatile("ds_read_b128 %0, %1 offset:6144" : "=v"(fa3) : "v"(aa));
;         __builtin_amdgcn_sched_barrier(0);
;         asm volatile("s_waitcnt lgkmcnt(3)" : "+v"(fb0), "+v"(fb1), "+v"(fa0));
;         acc[0][0][0] = mfma(fa0, fb0, acc[0][0][0]); acc[0][0][1] = mfma(fa0, fb1, acc[0][0][1]); __builtin_amdgcn_sched_barrier(0);
;         asm volatile("s_waitcnt lgkmcnt(2)" : "+v"(fa1));
;         acc[0][1][0] = mfma(fa1, fb0, acc[0][1][0]); acc[0][1][1] = mfma(fa1, fb1, acc[0][1][1]); __builtin_amdgcn_sched_barrier(0);
;         asm volatile("s_waitcnt lgkmcnt(1)" : "+v"(fa2));
;         acc[MI / 2 - 1][0][0] = mfma(fa2, fb0, acc[MI / 2 - 1][0][0]); acc[MI / 2 - 1][0][1] = mfma(fa2, fb1, acc[MI / 2 - 1][0][1]); __builtin_amdgcn_sched_barrier(0);
;         asm volatile("s_waitcnt lgkmcnt(0)" : "+v"(fa3));
;         acc[MI / 2 - 1][1][0] = mfma(fa3, fb0, acc[MI / 2 - 1][1][0]); acc[MI / 2 - 1][1][1] = mfma(fa3, fb1, acc[MI / 2 - 1][1][1]); __builtin_amdgcn_sched_barrier(0);
;       } else {
;         __builtin_amdgcn_sched_barrier(0);
;         asm volatile("s_waitcnt lgkmcnt(1)" : "+v"(fb0), "+v"(fb1), "+v"(fa0));
.Lhy2_issue_up:
	s_mul_i32 s99, s80, 0x6000
	s_setprio 1
	v_add_u32_e32 v149, s99, v138
	v_add_u32_e32 v176, s99, v141
	v_add_u32_e32 v172, v149, v145
	v_add_u32_e32 v156, v176, v145
	ds_read_b128 v[152:155], v156
	ds_read_b128 v[156:159], v156 offset:2048
	ds_read_b128 v[160:163], v172
	ds_read_b128 v[164:167], v172 offset:2048
	ds_read_b128 v[168:171], v172 offset:4096
	ds_read_b128 v[172:175], v172 offset:6144
	s_cmpk_eq_i32 s22, 0xf80
	s_cbranch_scc1 .Lhy2_noissue_up
	s_nop 0
	s_waitcnt lgkmcnt(3)
	s_nop 0
	v_mfma_f32_32x32x16_bf16 v[114:129], v[160:163], v[152:155], v[114:129]
	v_mfma_f32_32x32x16_bf16 v[98:113], v[160:163], v[156:159], v[98:113]
	s_mov_b32 m0, s84
	s_nop 0
	global_load_lds_dwordx4 v1, s[82:83]
	global_load_dwordx4 v[214:217], v1, s[82:83] offset:64
	s_add_u32 s82, s78, s22
	s_addc_u32 s83, s79, s23
	s_add_i32 s84, s58, s81
	s_mov_b32 m0, s84
	s_nop 0
	global_load_lds_dwordx4 v1, s[82:83]
	global_load_dwordx4 v[218:221], v1, s[82:83] offset:64
	s_waitcnt lgkmcnt(2)
	s_nop 0
	v_mfma_f32_32x32x16_bf16 v[82:97], v[164:167], v[152:155], v[82:97]
	v_mfma_f32_32x32x16_bf16 v[66:81], v[164:167], v[156:159], v[66:81]
	s_add_u32 s82, s76, s22
	s_addc_u32 s83, s77, s23
	s_add_i32 s84, s57, s81
	s_mov_b32 m0, s84
	s_nop 0
	global_load_lds_dwordx4 v1, s[82:83]
	global_load_dwordx4 v[222:225], v1, s[82:83] offset:64
	s_add_u32 s82, s74, s22
	s_addc_u32 s83, s75, s23
	s_add_i32 s84, s56, s81
	s_addk_i32 s81, 0x4000
	s_mov_b32 m0, s84
	s_nop 0
	global_load_lds_dwordx4 v1, s[82:83]
	global_load_dwordx4 v[226:229], v1, s[82:83] offset:64
	s_waitcnt lgkmcnt(1)
	s_nop 0
	v_mfma_f32_32x32x16_bf16 v[50:65], v[168:171], v[152:155], v[50:65]
	v_mfma_f32_32x32x16_bf16 v[34:49], v[168:171], v[156:159], v[34:49]
	s_add_u32 s82, s63, s22
	s_addc_u32 s83, s64, s23
	s_add_i32 s84, s81, s55
	s_mov_b32 m0, s84
	s_nop 0
	global_load_lds_dwordx4 v1, s[82:83]
	global_load_dwordx4 v[230:233], v1, s[82:83] offset:64
	s_add_u32 s82, s60, s22
	s_addc_u32 s83, s61, s23
	s_add_i32 s81, s81, s54
	s_mov_b32 m0, s81
	s_nop 0
	global_load_lds_dwordx4 v1, s[82:83]
	global_load_dwordx4 v[234:237], v1, s[82:83] offset:64
	s_waitcnt lgkmcnt(0)
	s_nop 0
	v_mfma_f32_32x32x16_bf16 v[18:33], v[172:175], v[152:155], v[18:33]
	v_mfma_f32_32x32x16_bf16 v[2:17], v[172:175], v[156:159], v[2:17]
	s_branch .Lhy2_after_up

; DEV f32x16 mfma(bf16x8 a, bf16x8 b, f32x16 c) { return __builtin_amdgcn_mfma_f32_32x32x16_bf16(a, b, c, 0, 0, 0); }
;     ...
;   for (int kt = 0; kt < nk; ++kt) {
;     if (kt + 1 < nk) { if (MI == 4) asm volatile("s_waitcnt vmcnt(6)" ::: "memory"); else asm volatile("s_waitcnt vmcnt(4)" ::: "memory"); } else asm volatile("s_waitcnt vmcnt(0)" ::: "memory");
;     __builtin_amdgcn_s_barrier();
;     if (kt + 2 < nk) { int s2 = stg + 2; if (s2 >= 3) s2 -= 3; g2_issue<MI>(ag + (size_t)(kt + 2) * 32, bg + (size_t)(kt + 2) * 32, lda, ldb, voffa, voffb, lds + s2 * G2_STAGE, w); }
;     const unsigned so = (unsigned)(stg * G2_STAGE);
;     __builtin_amdgcn_s_setprio(1);
; #pragma unroll
;     for (int ks = 0; ks < 2; ++ks) {
;       const unsigned aa = (ks ? la1 : la0) + so, bb = (ks ? lb1 : lb0) + so;
;       bf16x8 fb0, fb1, fa0, fa1, fa2, fa3;
;       asm volatile("ds_read_b128 %0, %1" : "=v"(fb0) : "v"(bb));
;       asm volatile("ds_read_b128 %0, %1 offset:2048" : "=v"(fb1) : "v"(bb));
;       asm volatile("ds_read_b128 %0, %1" : "=v"(fa0) : "v"(aa));
;       asm volatile("ds_read_b128 %0, %1 offset:2048" : "=v"(fa1) : "v"(aa));
;       if constexpr (MI == 4) {
;         asm volatile("ds_read_b128 %0, %1 offset:4096" : "=v"(fa2) : "v"(aa));
;         asm volatile("ds_read_b128 %0, %1 offset:6144" : "=v"(fa3) : "v"(aa));
;         __builtin_amdgcn_sched_barrier(0);
;         asm volatile("s_waitcnt lgkmcnt(3)" : "+v"(fb0), "+v"(fb1), "+v"(fa0));
;         acc[0][0][0] = mfma(fa0, fb0, acc[0][0][0]); acc[0][0][1] = mfma(fa0, fb1, acc[0][0][1]); __builtin_amdgcn_sched_barrier(0);
;         asm volatile("s_waitcnt lgkmcnt(2)" : "+v"(fa1));
;         acc[0][1][0] = mfma(fa1, fb0, acc[0][1][0]); acc[0][1][1] = mfma(fa1, fb1, acc[0][1][1]); __builtin_amdgcn_sched_barrier(0);
;         asm volatile("s_waitcnt lgkmcnt(1)" : "+v"(fa2));
;         acc[MI / 2 - 1][0][0] = mfma(fa2, fb0, acc[MI / 2 - 1][0][0]); acc[MI / 2 - 1][0][1] = mfma(fa2, fb1, acc[MI / 2 - 1][0][1]); __builtin_amdgcn_sched_barrier(0);
;         asm volatile("s_waitcnt lgkmcnt(0)" : "+v"(fa3));
;         acc[MI / 2 - 1][1][0] = mfma(fa3, fb0, acc[MI / 2 - 1][1][0]); acc[MI / 2 - 1][1][1] = mfma(fa3, fb1, acc[MI / 2 - 1][1][1]); __builtin_amdgcn_sched_barrier(0);
;       } else {
;         __builtin_amdgcn_sched_barrier(0);
;         asm volatile("s_waitcnt lgkmcnt(1)" : "+v"(fb0), "+v"(fb1), "+v"(fa0));
.Lhy2_after_up:
	v_add_u32_e32 v156, v176, v143
	v_add_u32_e32 v149, v149, v143
	ds_read_b128 v[152:155], v156
	ds_read_b128 v[156:159], v156 offset:2048
	ds_read_b128 v[160:163], v149
	ds_read_b128 v[164:167], v149 offset:2048
	ds_read_b128 v[168:171], v149 offset:4096
	ds_read_b128 v[172:175], v149 offset:6144
	s_nop 0
	s_waitcnt lgkmcnt(3)
	s_nop 0
	v_mfma_f32_32x32x16_bf16 v[114:129], v[160:163], v[152:155], v[114:129]
	v_mfma_f32_32x32x16_bf16 v[98:113], v[160:163], v[156:159], v[98:113]
	s_waitcnt lgkmcnt(2)
	s_nop 0
	v_mfma_f32_32x32x16_bf16 v[82:97], v[164:167], v[152:155], v[82:97]
	v_mfma_f32_32x32x16_bf16 v[66:81], v[164:167], v[156:159], v[66:81]
	s_waitcnt lgkmcnt(1)
	s_nop 0
	v_mfma_f32_32x32x16_bf16 v[50:65], v[168:171], v[152:155], v[50:65]
	v_mfma_f32_32x32x16_bf16 v[34:49], v[168:171], v[156:159], v[34:49]
	s_waitcnt lgkmcnt(0)
	s_nop 0
	v_mfma_f32_32x32x16_bf16 v[18:33], v[172:175], v[152:155], v[18:33]
	v_mfma_f32_32x32x16_bf16 v[2:17], v[172:175], v[156:159], v[2:17]
	s_setprio 0
	s_add_i32 s98, s80, 1
	s_cmp_lg_u32 s80, 2
	s_cselect_b32 s80, s98, 0
	s_waitcnt vmcnt(12)
	s_barrier
	s_mul_i32 s81, s80, 0x6000
	s_setprio 1
	v_add_u32_e32 v149, s81, v138
	v_add_u32_e32 v176, s81, v141
	v_add_u32_e32 v172, v149, v145
	v_add_u32_e32 v156, v176, v145
	ds_read_b128 v[152:155], v156
	ds_read_b128 v[156:159], v156 offset:2048
	ds_read_b128 v[160:163], v172
	ds_read_b128 v[164:167], v172 offset:2048
	ds_read_b128 v[168:171], v172 offset:4096
	ds_read_b128 v[172:175], v172 offset:6144
	s_nop 0
	s_waitcnt lgkmcnt(3)
	s_nop 0
	v_mfma_f32_32x32x16_bf16 v[114:129], v[160:163], v[152:155], v[114:129]
	v_mfma_f32_32x32x16_bf16 v[98:113], v[160:163], v[156:159], v[98:113]
	s_waitcnt lgkmcnt(2)
	s_nop 0
	v_mfma_f32_32x32x16_bf16 v[82:97], v[164:167], v[152:155], v[82:97]
	v_mfma_f32_32x32x16_bf16 v[66:81], v[164:167], v[156:159], v[66:81]
	s_waitcnt lgkmcnt(1)
	s_nop 0
	v_mfma_f32_32x32x16_bf16 v[50:65], v[168:171], v[152:155], v[50:65]
	v_mfma_f32_32x32x16_bf16 v[34:49], v[168:171], v[156:159], v[34:49]
	s_waitcnt lgkmcnt(0)
	s_nop 0
	v_mfma_f32_32x32x16_bf16 v[18:33], v[172:175], v[152:155], v[18:33]
	v_mfma_f32_32x32x16_bf16 v[2:17], v[172:175], v[156:159], v[2:17]
	v_add_u32_e32 v156, v176, v143
	v_add_u32_e32 v149, v149, v143
	ds_read_b128 v[152:155], v156
	ds_read_b128 v[156:159], v156 offset:2048
	ds_read_b128 v[160:163], v149
	ds_read_b128 v[164:167], v149 offset:2048
	ds_read_b128 v[168:171], v149 offset:4096
	ds_read_b128 v[172:175], v149 offset:6144
	s_nop 0
	s_waitcnt lgkmcnt(3)
	s_nop 0
	v_mfma_f32_32x32x16_bf16 v[114:129], v[160:163], v[152:155], v[114:129]
	v_mfma_f32_32x32x16_bf16 v[98:113], v[160:163], v[156:159], v[98:113]
	s_waitcnt lgkmcnt(2)
	s_nop 0
	v_mfma_f32_32x32x16_bf16 v[82:97], v[164:167], v[152:155], v[82:97]
	v_mfma_f32_32x32x16_bf16 v[66:81], v[164:167], v[156:159], v[66:81]
	s_waitcnt lgkmcnt(1)
	s_nop 0
	v_mfma_f32_32x32x16_bf16 v[50:65], v[168:171], v[152:155], v[50:65]
	v_mfma_f32_32x32x16_bf16 v[34:49], v[168:171], v[156:159], v[34:49]
	s_waitcnt lgkmcnt(0)
	s_nop 0
	v_mfma_f32_32x32x16_bf16 v[18:33], v[172:175], v[152:155], v[18:33]
	v_mfma_f32_32x32x16_bf16 v[2:17], v[172:175], v[156:159], v[2:17]
	s_add_i32 s98, s80, 1
	s_cmp_lg_u32 s80, 2
	s_cselect_b32 s80, s98, 0
	s_add_u32 s22, s22, 0x80
	s_addc_u32 s23, s23, 0
	s_cmpk_eq_i32 s22, 0x1000
	s_cbranch_scc0 .LBB0_118
	s_setprio 0
	s_and_b64 vcc, exec, s[8:9]
	s_waitcnt lgkmcnt(0)
	s_barrier
	s_cbranch_vccz .LBB0_109
	s_lshl_b32 s6, s52, 8
	s_ashr_i32 s7, s6, 31
	s_lshl_b32 s8, s53, 7
	s_lshl_b64 s[6:7], s[6:7], 12
	s_add_u32 s22, s26, s6
	s_addc_u32 s23, s27, s7
	s_ashr_i32 s9, s8, 31
	s_lshl_b64 s[6:7], s[8:9], 12
	s_add_u32 s60, s28, s6
	s_addc_u32 s61, s30, s7
	s_add_u32 s6, s22, s20
	s_addc_u32 s7, s23, s21
	s_add_u32 s8, s22, s18
	s_addc_u32 s9, s23, s19
	s_add_u32 s16, s22, s16
	s_addc_u32 s17, s23, s17
	s_add_u32 s14, s22, s14
	s_mov_b32 m0, s59
	s_nop 0
	global_load_lds_dwordx4 v1, s[6:7]
	s_addc_u32 s15, s23, s15
	s_mov_b32 m0, s58
	s_nop 0
	global_load_lds_dwordx4 v1, s[8:9]
	s_add_u32 s12, s60, s12
	s_mov_b32 m0, s57
	s_nop 0
	global_load_lds_dwordx4 v1, s[16:17]
	s_addc_u32 s13, s61, s13
	s_add_i32 s18, s55, 0x4000
	s_mov_b32 m0, s56
	s_nop 0
	global_load_lds_dwordx4 v1, s[14:15]
	s_add_u32 s10, s60, s10
	s_mov_b32 m0, s18
	s_nop 0
	global_load_lds_dwordx4 v1, s[12:13]
	s_addc_u32 s11, s61, s11
	s_add_i32 s18, s54, 0x4000
	s_add_u32 s6, s6, 64
	s_mov_b32 m0, s18
	s_nop 0
	global_load_lds_dwordx4 v1, s[10:11]
	s_addc_u32 s7, s7, 0
	s_add_i32 s18, s59, 0x6000
	s_mov_b32 m0, s18
	s_nop 0
	global_load_lds_dwordx4 v1, s[6:7]
	s_add_u32 s6, s8, 64
	s_addc_u32 s7, s9, 0
	s_add_i32 s8, s58, 0x6000
	s_mov_b32 m0, s8
	s_nop 0
	global_load_lds_dwordx4 v1, s[6:7]
	s_add_u32 s6, s16, 64
	s_addc_u32 s7, s17, 0
	s_add_i32 s8, s57, 0x6000
	s_mov_b32 m0, s8
	s_nop 0
	global_load_lds_dwordx4 v1, s[6:7]
	s_add_u32 s6, s14, 64
	s_addc_u32 s7, s15, 0
	s_add_i32 s8, s56, 0x6000
	s_mov_b32 m0, s8
	s_nop 0
	global_load_lds_dwordx4 v1, s[6:7]
	s_add_u32 s6, s12, 64
	s_addc_u32 s7, s13, 0
	s_add_i32 s55, s55, 0xa000
	s_mov_b32 m0, s55
	s_nop 0
	global_load_lds_dwordx4 v1, s[6:7]
	s_add_u32 s6, s10, 64
	s_addc_u32 s7, s11, 0
	s_add_i32 s54, s54, 0xa000
	s_mov_b32 m0, s54
	s_nop 0
	global_load_lds_dwordx4 v1, s[6:7]
	s_branch .LBB0_109

; DEV float bf2f(unsigned h) { return __uint_as_float(h << 16); }
; DEV void rowwise_row(int row, int lane, const bf16_t* __restrict__ add, const float* __restrict__ gpost, const float* __restrict__ xin,
;                      float* __restrict__ xout, const float* __restrict__ gpre, bf16_t* __restrict__ hin, float* __restrict__ fout) {
;   float4 xv[8];
;   const size_t base = (size_t)row * DM;
; #pragma unroll
;   for (int j = 0; j < 8; ++j) xv[j] = *(const float4*)(xin + base + j * 256 + lane * 4);
;   if (add) {
;     float4 av[8]; float ss = 0.f;
; #pragma unroll
;     for (int j = 0; j < 8; ++j) {
;       uint2 u = *(const uint2*)(add + base + j * 256 + lane * 4);
;       av[j] = make_float4(bf2f(u.x & 0xffffu), bf2f(u.x >> 16), bf2f(u.y & 0xffffu), bf2f(u.y >> 16));
;       ss += av[j].x * av[j].x + av[j].y * av[j].y + av[j].z * av[j].z + av[j].w * av[j].w;
;     }
;     ss = wave_sum(ss);
;     float rs = rsqrtf(ss * (1.f / DM) + EPS);
; #pragma unroll
;     for (int j = 0; j < 8; ++j) {
;       float4 g = *(const float4*)(gpost + j * 256 + lane * 4);
;       xv[j].x += av[j].x * rs * g.x; xv[j].y += av[j].y * rs * g.y; xv[j].z += av[j].z * rs * g.z; xv[j].w += av[j].w * rs * g.w;
;     }
;   }
.LBB0_129:
	v_ashrrev_i32_e32 v35, 31, v34
	s_mov_b64 s[6:7], s[70:71]
	v_lshlrev_b64 v[2:3], 12, v[34:35]
	v_lshlrev_b32_e32 v60, 1, v36
	v_lshl_add_u64 v[2:3], s[6:7], 0, v[2:3]
	v_mov_b32_e32 v61, v0
	v_lshl_add_u64 v[2:3], v[2:3], 0, v[60:61]
	s_mov_b64 s[6:7], 0x27bc8000
	s_mov_b64 s[4:5], s[70:71]
	v_lshl_add_u64 v[4:5], v[2:3], 0, s[6:7]
	flat_load_dwordx2 v[26:27], v[4:5] offset:512
	flat_load_dwordx2 v[28:29], v[4:5] offset:1024
	flat_load_dwordx2 v[30:31], v[4:5] offset:1536
	flat_load_dwordx2 v[32:33], v[4:5] offset:2048
	flat_load_dwordx2 v[62:63], v[4:5] offset:2560
	v_add_co_u32_e32 v2, vcc, s65, v2
	flat_load_dwordx2 v[64:65], v[4:5] offset:3072
	s_nop 0
	v_addc_co_u32_e32 v3, vcc, 0, v3, vcc
	flat_load_dwordx2 v[90:91], v[2:3]
	flat_load_dwordx2 v[92:93], v[4:5] offset:3584
	v_lshlrev_b64 v[18:19], 13, v[34:35]
	v_lshl_add_u64 v[106:107], v[38:39], 0, v[18:19]
	global_load_dwordx4 v[2:5], v[40:41], off
	global_load_dwordx4 v[6:9], v[40:41], off offset:1024
	global_load_dwordx4 v[10:13], v[40:41], off offset:2048
	global_load_dwordx4 v[14:17], v[40:41], off offset:3072
	global_load_dwordx4 v[66:69], v[42:43], off
	global_load_dwordx4 v[70:73], v[44:45], off
	flat_load_dwordx4 v[18:21], v[106:107]
	flat_load_dwordx4 v[22:25], v[106:107] offset:1024
	flat_load_dwordx4 v[74:77], v[106:107] offset:2048
	flat_load_dwordx4 v[78:81], v[106:107] offset:3072
	v_cmp_lt_i32_e32 vcc, v203, v202
	s_movk_i32 s6, 0x1000
	s_waitcnt vmcnt(0) lgkmcnt(0)
	v_lshlrev_b32_e32 v110, 16, v26
	v_cndmask_b32_e32 v1, v200, v203, vcc
	v_add_co_u32_e32 v108, vcc, s6, v106
	v_and_b32_e32 v123, 0xffff0000, v32
	s_nop 0
	v_addc_co_u32_e32 v109, vcc, 0, v107, vcc
	v_and_b32_e32 v127, 0xffff0000, v62
	flat_load_dwordx4 v[82:85], v[108:109]
	flat_load_dwordx4 v[86:89], v[108:109] offset:1024
	v_lshlrev_b32_e32 v122, 16, v32
	v_lshlrev_b32_e32 v126, 16, v62
	v_mov_b32_e32 v96, v123
	v_mov_b32_e32 v97, v127
	v_lshlrev_b32_e32 v124, 16, v33
	v_lshlrev_b32_e32 v128, 16, v63
	v_mov_b32_e32 v94, v122
	v_mov_b32_e32 v95, v126
	v_pk_mul_f32 v[96:97], v[96:97], v[96:97]
	v_and_b32_e32 v111, 0xffff0000, v26
	v_lshlrev_b32_e32 v112, 16, v27
	v_and_b32_e32 v113, 0xffff0000, v27
	v_lshlrev_b32_e32 v114, 16, v28
	v_and_b32_e32 v115, 0xffff0000, v28
	v_lshlrev_b32_e32 v116, 16, v29
	v_and_b32_e32 v117, 0xffff0000, v29
	v_and_b32_e32 v125, 0xffff0000, v33
	v_and_b32_e32 v129, 0xffff0000, v63
	v_lshlrev_b32_e32 v26, 16, v90
	v_and_b32_e32 v27, 0xffff0000, v90
	v_lshlrev_b32_e32 v28, 16, v91
	v_and_b32_e32 v29, 0xffff0000, v91
	v_mov_b32_e32 v90, v124
	v_mov_b32_e32 v91, v128
	v_pk_fma_f32 v[94:95], v[94:95], v[94:95], v[96:97]
	v_lshlrev_b32_e32 v156, 16, v92
	v_and_b32_e32 v157, 0xffff0000, v92
	v_lshlrev_b32_e32 v158, 16, v93
	v_and_b32_e32 v159, 0xffff0000, v93
	v_mov_b32_e32 v92, v125
	v_mov_b32_e32 v93, v129
	v_pk_fma_f32 v[90:91], v[90:91], v[90:91], v[94:95]
	v_pk_mul_f32 v[32:33], v[110:111], v[110:111]
	v_pk_fma_f32 v[168:169], v[92:93], v[92:93], v[90:91]
	flat_load_dwordx4 v[90:93], v[108:109] offset:2048
	flat_load_dwordx4 v[94:97], v[108:109] offset:3072
	global_load_dwordx4 v[98:101], v[46:47], off
	global_load_dwordx4 v[102:105], v[48:49], off
	v_lshlrev_b32_e32 v118, 16, v30
	v_and_b32_e32 v119, 0xffff0000, v30
	v_lshlrev_b32_e32 v120, 16, v31
	v_and_b32_e32 v121, 0xffff0000, v31
	v_pk_mul_f32 v[30:31], v[112:113], v[112:113]
	v_pk_mul_f32 v[166:167], v[26:27], v[26:27]
	v_add_f32_e32 v32, v32, v33
	v_lshlrev_b32_e32 v152, 16, v64
	v_and_b32_e32 v153, 0xffff0000, v64
	v_lshlrev_b32_e32 v154, 16, v65
	v_and_b32_e32 v155, 0xffff0000, v65
	v_pk_mul_f32 v[64:65], v[114:115], v[114:115]
	v_pk_mul_f32 v[164:165], v[28:29], v[28:29]
	v_add_f32_e32 v37, v166, v167
	v_add_f32_e32 v30, v32, v30
	v_pk_mul_f32 v[62:63], v[116:117], v[116:117]
	v_add_f32_e32 v37, v37, v164
	v_add_f32_e32 v30, v31, v30
	v_add_f32_e32 v31, v64, v65
	v_add_f32_e32 v37, v165, v37
	v_add_f32_e32 v31, v31, v62
	v_pk_mul_f32 v[162:163], v[118:119], v[118:119]
	v_add_f32_e32 v30, v37, v30
	v_add_f32_e32 v31, v63, v31
	v_pk_mul_f32 v[160:161], v[120:121], v[120:121]
	v_add_f32_e32 v30, v30, v31
	v_add_f32_e32 v31, v162, v163
	v_mov_b32_e32 v176, v153
	v_mov_b32_e32 v177, v157
	v_add_f32_e32 v31, v31, v160
	v_mov_b32_e32 v174, v152
	v_mov_b32_e32 v175, v156
	v_pk_mul_f32 v[176:177], v[176:177], v[176:177]
	v_add_f32_e32 v31, v161, v31
	v_mov_b32_e32 v170, v154
	v_mov_b32_e32 v171, v158
	v_pk_fma_f32 v[174:175], v[174:175], v[174:175], v[176:177]
	v_add_f32_e32 v30, v30, v31
	v_mov_b32_e32 v172, v155
	v_mov_b32_e32 v173, v159
	v_pk_fma_f32 v[170:171], v[170:171], v[170:171], v[174:175]
	v_add_f32_e32 v30, v30, v168
	v_pk_fma_f32 v[170:171], v[172:173], v[172:173], v[170:171]
	v_add_f32_e32 v30, v30, v169
	v_add_f32_e32 v30, v30, v170
	v_lshlrev_b32_e32 v1, 2, v1
	v_add_f32_e32 v30, v30, v171
	ds_bpermute_b32 v31, v1, v30
	v_cmp_lt_i32_e32 vcc, v204, v202
	v_readlane_b32 s6, v240, 61
	v_readlane_b32 s7, v240, 62
	v_cndmask_b32_e32 v32, v200, v204, vcc
	v_lshlrev_b32_e32 v37, 2, v32
	s_waitcnt lgkmcnt(0)
	v_add_f32_e32 v30, v30, v31
	ds_bpermute_b32 v31, v37, v30
	v_cmp_lt_i32_e32 vcc, v205, v202
	s_waitcnt lgkmcnt(0)
	v_add_f32_e32 v30, v30, v31
	v_cndmask_b32_e32 v32, v200, v205, vcc
	v_lshlrev_b32_e32 v62, 2, v32
	ds_bpermute_b32 v31, v62, v30
	v_cmp_lt_i32_e32 vcc, v206, v202
	s_waitcnt lgkmcnt(0)
	v_add_f32_e32 v30, v30, v31
	v_cndmask_b32_e32 v32, v200, v206, vcc
	v_lshlrev_b32_e32 v63, 2, v32
	ds_bpermute_b32 v31, v63, v30
	v_cmp_lt_i32_e32 vcc, v207, v202
	s_waitcnt lgkmcnt(0)
	v_add_f32_e32 v30, v30, v31
	v_cndmask_b32_e32 v32, v200, v207, vcc
	v_lshlrev_b32_e32 v64, 2, v32
	ds_bpermute_b32 v31, v64, v30
	v_cmp_lt_i32_e32 vcc, v208, v202
	s_waitcnt lgkmcnt(0)
; DEV void rowwise_row(int row, int lane, const bf16_t* __restrict__ add, const float* __restrict__ gpost, const float* __restrict__ xin,
;                      float* __restrict__ xout, const float* __restrict__ gpre, bf16_t* __restrict__ hin, float* __restrict__ fout) {
;     ...
;       ss += av[j].x * av[j].x + av[j].y * av[j].y + av[j].z * av[j].z + av[j].w * av[j].w;
;     }
;     ss = wave_sum(ss);
;     float rs = rsqrtf(ss * (1.f / DM) + EPS);
; #pragma unroll
;     for (int j = 0; j < 8; ++j) {
;       float4 g = *(const float4*)(gpost + j * 256 + lane * 4);
;       xv[j].x += av[j].x * rs * g.x; xv[j].y += av[j].y * rs * g.y; xv[j].z += av[j].z * rs * g.z; xv[j].w += av[j].w * rs * g.w;
;     }
;   }
;   if (xout) {
; #pragma unroll
;     for (int j = 0; j < 8; ++j) *(float4*)(xout + base + j * 256 + lane * 4) = xv[j];
;   }
;   if (fout) {
; #pragma unroll
;     for (int j = 0; j < 8; ++j) *(float4*)(fout + base + j * 256 + lane * 4) = xv[j];
	v_add_f32_e32 v30, v30, v31
	v_cndmask_b32_e32 v32, v200, v208, vcc
	v_lshlrev_b32_e32 v65, 2, v32
	ds_bpermute_b32 v31, v65, v30
	s_waitcnt lgkmcnt(0)
	v_add_f32_e32 v30, v30, v31
	v_fmamk_f32 v30, v30, 0x3a000000, v195
	v_mul_f32_e32 v31, 0x4b800000, v30
	v_cmp_gt_f32_e32 vcc, s38, v30
	s_nop 1
	v_cndmask_b32_e32 v30, v30, v31, vcc
	v_rsq_f32_e32 v30, v30
	s_nop 0
	v_mul_f32_e32 v31, 0x45800000, v30
	v_cndmask_b32_e32 v130, v30, v31, vcc
	v_pk_mul_f32 v[26:27], v[130:131], v[26:27] op_sel_hi:[0,1]
	v_pk_fma_f32 v[30:31], v[2:3], v[26:27], v[18:19]
	v_pk_mul_f32 v[2:3], v[130:131], v[28:29] op_sel_hi:[0,1]
	v_pk_fma_f32 v[32:33], v[4:5], v[2:3], v[20:21]
	v_pk_mul_f32 v[2:3], v[130:131], v[110:111] op_sel_hi:[0,1]
	v_pk_fma_f32 v[26:27], v[6:7], v[2:3], v[22:23]
	v_pk_mul_f32 v[2:3], v[130:131], v[112:113] op_sel_hi:[0,1]
	v_pk_fma_f32 v[28:29], v[8:9], v[2:3], v[24:25]
	v_pk_mul_f32 v[2:3], v[130:131], v[114:115] op_sel_hi:[0,1]
	v_pk_fma_f32 v[22:23], v[10:11], v[2:3], v[74:75]
	v_pk_mul_f32 v[2:3], v[130:131], v[116:117] op_sel_hi:[0,1]
	v_pk_fma_f32 v[24:25], v[12:13], v[2:3], v[76:77]
	v_pk_mul_f32 v[2:3], v[130:131], v[118:119] op_sel_hi:[0,1]
	v_pk_fma_f32 v[18:19], v[2:3], v[14:15], v[78:79]
	v_pk_mul_f32 v[2:3], v[130:131], v[120:121] op_sel_hi:[0,1]
	v_pk_fma_f32 v[20:21], v[2:3], v[16:17], v[80:81]
	v_pk_mul_f32 v[2:3], v[130:131], v[122:123] op_sel_hi:[0,1]
	s_waitcnt vmcnt(0)
	v_pk_fma_f32 v[14:15], v[2:3], v[66:67], v[82:83]
	v_pk_mul_f32 v[2:3], v[130:131], v[124:125] op_sel_hi:[0,1]
	v_pk_fma_f32 v[16:17], v[2:3], v[68:69], v[84:85]
	v_pk_mul_f32 v[2:3], v[130:131], v[126:127] op_sel_hi:[0,1]
	v_pk_fma_f32 v[10:11], v[2:3], v[70:71], v[86:87]
	v_pk_mul_f32 v[2:3], v[130:131], v[128:129] op_sel_hi:[0,1]
	v_pk_fma_f32 v[12:13], v[2:3], v[72:73], v[88:89]
	v_pk_mul_f32 v[2:3], v[130:131], v[152:153] op_sel_hi:[0,1]
	v_pk_fma_f32 v[6:7], v[2:3], v[98:99], v[90:91]
	v_pk_mul_f32 v[2:3], v[130:131], v[154:155] op_sel_hi:[0,1]
	v_pk_fma_f32 v[8:9], v[2:3], v[100:101], v[92:93]
	v_pk_mul_f32 v[2:3], v[130:131], v[156:157] op_sel_hi:[0,1]
	v_pk_mul_f32 v[4:5], v[130:131], v[158:159] op_sel_hi:[0,1]
	v_pk_fma_f32 v[2:3], v[2:3], v[102:103], v[94:95]
	v_pk_fma_f32 v[4:5], v[4:5], v[104:105], v[96:97]
	s_andn2_b64 vcc, exec, s[6:7]
	flat_store_dwordx4 v[106:107], v[30:33]
	flat_store_dwordx4 v[106:107], v[26:29] offset:1024
	flat_store_dwordx4 v[106:107], v[22:25] offset:2048
	flat_store_dwordx4 v[106:107], v[18:21] offset:3072
	flat_store_dwordx4 v[108:109], v[14:17]
	flat_store_dwordx4 v[108:109], v[10:13] offset:1024
	flat_store_dwordx4 v[108:109], v[6:9] offset:2048
	flat_store_dwordx4 v[108:109], v[2:5] offset:3072
	s_cbranch_vccnz .LBB0_128
; DEV void rowwise_row(int row, int lane, const bf16_t* __restrict__ add, const float* __restrict__ gpost, const float* __restrict__ xin,
;                      float* __restrict__ xout, const float* __restrict__ gpre, bf16_t* __restrict__ hin, float* __restrict__ fout) {
;     ...
;   if (gpre) {
;     float ss = 0.f;
; #pragma unroll
;     for (int j = 0; j < 8; ++j) ss += xv[j].x * xv[j].x + xv[j].y * xv[j].y + xv[j].z * xv[j].z + xv[j].w * xv[j].w;
;     ss = wave_sum(ss);
;     float rs = rsqrtf(ss * (1.f / DM) + EPS);
; #pragma unroll
;     for (int j = 0; j < 8; ++j) {
;       float4 g = *(const float4*)(gpre + j * 256 + lane * 4);
;       uint2 o; o.x = cvtpk(xv[j].x * rs * g.x, xv[j].y * rs * g.y); o.y = cvtpk(xv[j].z * rs * g.z, xv[j].w * rs * g.w);
;       *(uint2*)(hin + base + j * 256 + lane * 4) = o;
;     }
	v_pk_mul_f32 v[68:69], v[30:31], v[30:31]
	v_pk_mul_f32 v[72:73], v[26:27], v[26:27]
	v_lshlrev_b64 v[66:67], 11, v[34:35]
	v_pk_mul_f32 v[70:71], v[32:33], v[32:33]
	v_pk_mul_f32 v[74:75], v[28:29], v[28:29]
	v_add_f32_e32 v35, v72, v73
	v_add_f32_e32 v68, v68, v69
	v_add_f32_e32 v35, v74, v35
	v_add_f32_e32 v68, v70, v68
	v_pk_mul_f32 v[76:77], v[22:23], v[22:23]
	v_add_f32_e32 v35, v75, v35
	v_add_f32_e32 v68, v71, v68
	v_pk_mul_f32 v[78:79], v[24:25], v[24:25]
	v_add_f32_e32 v35, v68, v35
	v_add_f32_e32 v68, v76, v77
	v_mov_b32_e32 v86, v15
	v_mov_b32_e32 v87, v11
	v_add_f32_e32 v68, v78, v68
	v_pk_mul_f32 v[80:81], v[18:19], v[18:19]
	v_mov_b32_e32 v84, v14
	v_mov_b32_e32 v85, v10
	v_pk_mul_f32 v[86:87], v[86:87], v[86:87]
	v_add_f32_e32 v68, v79, v68
	v_pk_mul_f32 v[82:83], v[20:21], v[20:21]
	v_pk_fma_f32 v[84:85], v[84:85], v[84:85], v[86:87]
	v_mov_b32_e32 v86, v16
	v_mov_b32_e32 v87, v12
	v_add_f32_e32 v35, v68, v35
	v_add_f32_e32 v68, v80, v81
	v_pk_fma_f32 v[84:85], v[86:87], v[86:87], v[84:85]
	v_mov_b32_e32 v86, v17
	v_mov_b32_e32 v87, v13
	v_mov_b32_e32 v88, v7
	v_mov_b32_e32 v89, v3
	v_add_f32_e32 v68, v68, v82
	v_pk_fma_f32 v[84:85], v[86:87], v[86:87], v[84:85]
	v_mov_b32_e32 v86, v6
	v_mov_b32_e32 v87, v2
	v_pk_mul_f32 v[88:89], v[88:89], v[88:89]
	v_add_f32_e32 v68, v68, v83
	v_pk_fma_f32 v[86:87], v[86:87], v[86:87], v[88:89]
	v_mov_b32_e32 v88, v8
	v_mov_b32_e32 v89, v4
	v_add_f32_e32 v35, v35, v68
	v_pk_fma_f32 v[86:87], v[88:89], v[88:89], v[86:87]
	v_mov_b32_e32 v88, v9
	v_mov_b32_e32 v89, v5
	v_add_f32_e32 v35, v35, v84
	v_pk_fma_f32 v[86:87], v[88:89], v[88:89], v[86:87]
	v_add_f32_e32 v35, v35, v85
	v_add_f32_e32 v35, v35, v86
	v_add_f32_e32 v35, v35, v87
	ds_bpermute_b32 v1, v1, v35
	s_waitcnt lgkmcnt(0)
	v_add_f32_e32 v1, v35, v1
	ds_bpermute_b32 v35, v37, v1
	s_waitcnt lgkmcnt(0)
	v_add_f32_e32 v1, v1, v35
	ds_bpermute_b32 v35, v62, v1
	s_waitcnt lgkmcnt(0)
	v_add_f32_e32 v1, v1, v35
	ds_bpermute_b32 v35, v63, v1
	s_waitcnt lgkmcnt(0)
	v_add_f32_e32 v1, v1, v35
	ds_bpermute_b32 v35, v64, v1
	s_waitcnt lgkmcnt(0)
	v_add_f32_e32 v1, v1, v35
	ds_bpermute_b32 v35, v65, v1
	v_lshl_add_u64 v[64:65], v[66:67], 1, s[4:5]
	v_lshl_add_u64 v[68:69], v[64:65], 0, v[60:61]
	global_load_dwordx4 v[64:67], v[50:51], off
	global_load_dwordx4 v[178:181], v[50:51], off offset:1024
	global_load_dwordx4 v[182:185], v[50:51], off offset:2048
	global_load_dwordx4 v[186:189], v[50:51], off offset:3072
	global_load_dwordx4 v[214:217], v[52:53], off
	global_load_dwordx4 v[218:221], v[54:55], off
	global_load_dwordx4 v[222:225], v[56:57], off
	global_load_dwordx4 v[226:229], v[58:59], off
	s_mov_b64 s[4:5], 0x1d6e0000
	s_waitcnt lgkmcnt(0)
	v_add_f32_e32 v1, v1, v35
	v_fmamk_f32 v1, v1, 0x3a000000, v195
	v_cmp_gt_f32_e32 vcc, s38, v1
	v_mul_f32_e32 v35, 0x4b800000, v1
	v_lshl_add_u64 v[60:61], v[68:69], 0, s[4:5]
	v_cndmask_b32_e32 v1, v1, v35, vcc
	v_rsq_f32_e32 v1, v1
	s_mov_b32 s4, 0x1d6e0000
	v_mul_f32_e32 v35, 0x45800000, v1
	v_cndmask_b32_e32 v62, v1, v35, vcc
	v_pk_mul_f32 v[30:31], v[30:31], v[62:63] op_sel_hi:[1,0]
	v_pk_mul_f32 v[32:33], v[32:33], v[62:63] op_sel_hi:[1,0]
	v_pk_mul_f32 v[26:27], v[26:27], v[62:63] op_sel_hi:[1,0]
	v_pk_mul_f32 v[28:29], v[28:29], v[62:63] op_sel_hi:[1,0]
	v_pk_mul_f32 v[22:23], v[22:23], v[62:63] op_sel_hi:[1,0]
	v_pk_mul_f32 v[24:25], v[24:25], v[62:63] op_sel_hi:[1,0]
	v_pk_mul_f32 v[18:19], v[18:19], v[62:63] op_sel_hi:[1,0]
	v_pk_mul_f32 v[20:21], v[20:21], v[62:63] op_sel_hi:[1,0]
	v_pk_mul_f32 v[14:15], v[14:15], v[62:63] op_sel_hi:[1,0]
	v_pk_mul_f32 v[16:17], v[16:17], v[62:63] op_sel_hi:[1,0]
	v_pk_mul_f32 v[10:11], v[10:11], v[62:63] op_sel_hi:[1,0]
	v_pk_mul_f32 v[12:13], v[12:13], v[62:63] op_sel_hi:[1,0]
	v_pk_mul_f32 v[6:7], v[6:7], v[62:63] op_sel_hi:[1,0]
	v_pk_mul_f32 v[8:9], v[8:9], v[62:63] op_sel_hi:[1,0]
	v_pk_mul_f32 v[2:3], v[2:3], v[62:63] op_sel_hi:[1,0]
	v_pk_mul_f32 v[4:5], v[4:5], v[62:63] op_sel_hi:[1,0]
	s_waitcnt vmcnt(0)
	v_pk_mul_f32 v[30:31], v[64:65], v[30:31]
	v_pk_mul_f32 v[32:33], v[66:67], v[32:33]
	v_cvt_pk_bf16_f32 v30, v30, v31
	v_cvt_pk_bf16_f32 v31, v32, v33
	v_add_co_u32_e32 v32, vcc, s4, v68
	s_nop 1
	v_addc_co_u32_e32 v33, vcc, 0, v69, vcc
	flat_store_dwordx2 v[32:33], v[30:31]
	v_mov_b32_e32 v30, v178
	v_mov_b32_e32 v31, v179
	v_mov_b32_e32 v32, v180
	v_mov_b32_e32 v33, v181
	s_nop 0
	v_pk_mul_f32 v[26:27], v[30:31], v[26:27]
	v_pk_mul_f32 v[28:29], v[32:33], v[28:29]
	v_cvt_pk_bf16_f32 v26, v26, v27
	v_cvt_pk_bf16_f32 v27, v28, v29
	flat_store_dwordx2 v[60:61], v[26:27] offset:512
	v_mov_b32_e32 v26, v182
	v_mov_b32_e32 v27, v183
	v_mov_b32_e32 v28, v184
	v_mov_b32_e32 v29, v185
	s_nop 0
	v_pk_mul_f32 v[22:23], v[22:23], v[26:27]
	v_pk_mul_f32 v[24:25], v[24:25], v[28:29]
	v_cvt_pk_bf16_f32 v22, v22, v23
	v_cvt_pk_bf16_f32 v23, v24, v25
	flat_store_dwordx2 v[60:61], v[22:23] offset:1024
	v_mov_b32_e32 v22, v186
	v_mov_b32_e32 v23, v187
	v_mov_b32_e32 v24, v188
	v_mov_b32_e32 v25, v189
	s_nop 0
	v_pk_mul_f32 v[18:19], v[18:19], v[22:23]
	v_pk_mul_f32 v[20:21], v[20:21], v[24:25]
	v_cvt_pk_bf16_f32 v18, v18, v19
	v_cvt_pk_bf16_f32 v19, v20, v21
	flat_store_dwordx2 v[60:61], v[18:19] offset:1536
	v_mov_b32_e32 v18, v214
	v_mov_b32_e32 v19, v215
	v_mov_b32_e32 v20, v216
	v_mov_b32_e32 v21, v217
	s_nop 0
	v_pk_mul_f32 v[14:15], v[14:15], v[18:19]
	v_pk_mul_f32 v[16:17], v[16:17], v[20:21]
	v_cvt_pk_bf16_f32 v14, v14, v15
	v_cvt_pk_bf16_f32 v15, v16, v17
	flat_store_dwordx2 v[60:61], v[14:15] offset:2048
	v_mov_b32_e32 v14, v218
	v_mov_b32_e32 v15, v219
	v_mov_b32_e32 v16, v220
	v_mov_b32_e32 v17, v221
	s_nop 0
	v_pk_mul_f32 v[10:11], v[10:11], v[14:15]
	v_pk_mul_f32 v[12:13], v[12:13], v[16:17]
	v_cvt_pk_bf16_f32 v10, v10, v11
	v_cvt_pk_bf16_f32 v11, v12, v13
	flat_store_dwordx2 v[60:61], v[10:11] offset:2560
	v_mov_b32_e32 v10, v222
	v_mov_b32_e32 v11, v223
	v_mov_b32_e32 v12, v224
	v_mov_b32_e32 v13, v225
	s_nop 0
	v_pk_mul_f32 v[6:7], v[6:7], v[10:11]
	v_pk_mul_f32 v[8:9], v[8:9], v[12:13]
	v_cvt_pk_bf16_f32 v6, v6, v7
	v_cvt_pk_bf16_f32 v7, v8, v9
	flat_store_dwordx2 v[60:61], v[6:7] offset:3072
	v_mov_b32_e32 v6, v226
	v_mov_b32_e32 v7, v227
	v_mov_b32_e32 v8, v228
	v_mov_b32_e32 v9, v229
	s_nop 0
	v_pk_mul_f32 v[2:3], v[2:3], v[6:7]
	v_pk_mul_f32 v[4:5], v[4:5], v[8:9]
	v_cvt_pk_bf16_f32 v2, v2, v3
	v_cvt_pk_bf16_f32 v3, v4, v5
	flat_store_dwordx2 v[60:61], v[2:3] offset:3584
	s_branch .LBB0_128

; DEV f32x16 mfma(bf16x8 a, bf16x8 b, f32x16 c) { return __builtin_amdgcn_mfma_f32_32x32x16_bf16(a, b, c, 0, 0, 0); }
;     ...
;   for (int kt = 0; kt < nk; ++kt) {
;     if (kt + 1 < nk) { if (MI == 4) asm volatile("s_waitcnt vmcnt(6)" ::: "memory"); else asm volatile("s_waitcnt vmcnt(4)" ::: "memory"); } else asm volatile("s_waitcnt vmcnt(0)" ::: "memory");
;     __builtin_amdgcn_s_barrier();
;     if (kt + 2 < nk) { int s2 = stg + 2; if (s2 >= 3) s2 -= 3; g2_issue<MI>(ag + (size_t)(kt + 2) * 32, bg + (size_t)(kt + 2) * 32, lda, ldb, voffa, voffb, lds + s2 * G2_STAGE, w); }
;     const unsigned so = (unsigned)(stg * G2_STAGE);
;     __builtin_amdgcn_s_setprio(1);
; #pragma unroll
;     for (int ks = 0; ks < 2; ++ks) {
;       const unsigned aa = (ks ? la1 : la0) + so, bb = (ks ? lb1 : lb0) + so;
;       bf16x8 fb0, fb1, fa0, fa1, fa2, fa3;
;       asm volatile("ds_read_b128 %0, %1" : "=v"(fb0) : "v"(bb));
;       asm volatile("ds_read_b128 %0, %1 offset:2048" : "=v"(fb1) : "v"(bb));
;       asm volatile("ds_read_b128 %0, %1" : "=v"(fa0) : "v"(aa));
;       asm volatile("ds_read_b128 %0, %1 offset:2048" : "=v"(fa1) : "v"(aa));
;       if constexpr (MI == 4) {
;         asm volatile("ds_read_b128 %0, %1 offset:4096" : "=v"(fa2) : "v"(aa));
;         asm volatile("ds_read_b128 %0, %1 offset:6144" : "=v"(fa3) : "v"(aa));
;         __builtin_amdgcn_sched_barrier(0);
;         asm volatile("s_waitcnt lgkmcnt(3)" : "+v"(fb0), "+v"(fb1), "+v"(fa0));
;         acc[0][0][0] = mfma(fa0, fb0, acc[0][0][0]); acc[0][0][1] = mfma(fa0, fb1, acc[0][0][1]); __builtin_amdgcn_sched_barrier(0);
;         asm volatile("s_waitcnt lgkmcnt(2)" : "+v"(fa1));
;         acc[0][1][0] = mfma(fa1, fb0, acc[0][1][0]); acc[0][1][1] = mfma(fa1, fb1, acc[0][1][1]); __builtin_amdgcn_sched_barrier(0);
;         asm volatile("s_waitcnt lgkmcnt(1)" : "+v"(fa2));
;         acc[MI / 2 - 1][0][0] = mfma(fa2, fb0, acc[MI / 2 - 1][0][0]); acc[MI / 2 - 1][0][1] = mfma(fa2, fb1, acc[MI / 2 - 1][0][1]); __builtin_amdgcn_sched_barrier(0);
;         asm volatile("s_waitcnt lgkmcnt(0)" : "+v"(fa3));
;         acc[MI / 2 - 1][1][0] = mfma(fa3, fb0, acc[MI / 2 - 1][1][0]); acc[MI / 2 - 1][1][1] = mfma(fa3, fb1, acc[MI / 2 - 1][1][1]); __builtin_amdgcn_sched_barrier(0);
;       } else {
;         __builtin_amdgcn_sched_barrier(0);
;         asm volatile("s_waitcnt lgkmcnt(1)" : "+v"(fb0), "+v"(fb1), "+v"(fa0));
.Lhy2_after_proj:
	v_add_u32_e32 v156, v176, v143
	v_add_u32_e32 v149, v149, v143
	ds_read_b128 v[152:155], v156
	ds_read_b128 v[156:159], v156 offset:2048
	ds_read_b128 v[160:163], v149
	ds_read_b128 v[164:167], v149 offset:2048
	ds_read_b128 v[168:171], v149 offset:4096
	ds_read_b128 v[172:175], v149 offset:6144
	s_nop 0
	s_waitcnt lgkmcnt(3)
	s_nop 0
	v_mfma_f32_32x32x16_bf16 v[114:129], v[160:163], v[152:155], v[114:129]
	v_mfma_f32_32x32x16_bf16 v[98:113], v[160:163], v[156:159], v[98:113]
	s_waitcnt lgkmcnt(2)
	s_nop 0
	v_mfma_f32_32x32x16_bf16 v[82:97], v[164:167], v[152:155], v[82:97]
	v_mfma_f32_32x32x16_bf16 v[66:81], v[164:167], v[156:159], v[66:81]
	s_waitcnt lgkmcnt(1)
	s_nop 0
	v_mfma_f32_32x32x16_bf16 v[50:65], v[168:171], v[152:155], v[50:65]
	v_mfma_f32_32x32x16_bf16 v[34:49], v[168:171], v[156:159], v[34:49]
	s_waitcnt lgkmcnt(0)
	s_nop 0
	v_mfma_f32_32x32x16_bf16 v[18:33], v[172:175], v[152:155], v[18:33]
	v_mfma_f32_32x32x16_bf16 v[2:17], v[172:175], v[156:159], v[2:17]
	s_setprio 0
	s_add_i32 s98, s80, 1
	s_cmp_lg_u32 s80, 2
	s_cselect_b32 s80, s98, 0
	s_waitcnt vmcnt(12)
	s_barrier
	s_mul_i32 s81, s80, 0x6000
	s_setprio 1
	v_add_u32_e32 v149, s81, v138
	v_add_u32_e32 v176, s81, v141
	v_add_u32_e32 v172, v149, v145
	v_add_u32_e32 v156, v176, v145
	ds_read_b128 v[152:155], v156
	ds_read_b128 v[156:159], v156 offset:2048
	ds_read_b128 v[160:163], v172
	ds_read_b128 v[164:167], v172 offset:2048
	ds_read_b128 v[168:171], v172 offset:4096
	ds_read_b128 v[172:175], v172 offset:6144
	s_nop 0
	s_waitcnt lgkmcnt(3)
	s_nop 0
	v_mfma_f32_32x32x16_bf16 v[114:129], v[160:163], v[152:155], v[114:129]
	v_mfma_f32_32x32x16_bf16 v[98:113], v[160:163], v[156:159], v[98:113]
	s_waitcnt lgkmcnt(2)
	s_nop 0
	v_mfma_f32_32x32x16_bf16 v[82:97], v[164:167], v[152:155], v[82:97]
	v_mfma_f32_32x32x16_bf16 v[66:81], v[164:167], v[156:159], v[66:81]
	s_waitcnt lgkmcnt(1)
	s_nop 0
	v_mfma_f32_32x32x16_bf16 v[50:65], v[168:171], v[152:155], v[50:65]
	v_mfma_f32_32x32x16_bf16 v[34:49], v[168:171], v[156:159], v[34:49]
	s_waitcnt lgkmcnt(0)
	s_nop 0
	v_mfma_f32_32x32x16_bf16 v[18:33], v[172:175], v[152:155], v[18:33]
	v_mfma_f32_32x32x16_bf16 v[2:17], v[172:175], v[156:159], v[2:17]
	v_add_u32_e32 v156, v176, v143
	v_add_u32_e32 v149, v149, v143
	ds_read_b128 v[152:155], v156
	ds_read_b128 v[156:159], v156 offset:2048
	ds_read_b128 v[160:163], v149
	ds_read_b128 v[164:167], v149 offset:2048
	ds_read_b128 v[168:171], v149 offset:4096
	ds_read_b128 v[172:175], v149 offset:6144
	s_nop 0
	s_waitcnt lgkmcnt(3)
	s_nop 0
	v_mfma_f32_32x32x16_bf16 v[114:129], v[160:163], v[152:155], v[114:129]
	v_mfma_f32_32x32x16_bf16 v[98:113], v[160:163], v[156:159], v[98:113]
	s_waitcnt lgkmcnt(2)
	s_nop 0
	v_mfma_f32_32x32x16_bf16 v[82:97], v[164:167], v[152:155], v[82:97]
	v_mfma_f32_32x32x16_bf16 v[66:81], v[164:167], v[156:159], v[66:81]
	s_waitcnt lgkmcnt(1)
	s_nop 0
	v_mfma_f32_32x32x16_bf16 v[50:65], v[168:171], v[152:155], v[50:65]
	v_mfma_f32_32x32x16_bf16 v[34:49], v[168:171], v[156:159], v[34:49]
	s_waitcnt lgkmcnt(0)
	s_nop 0
	v_mfma_f32_32x32x16_bf16 v[18:33], v[172:175], v[152:155], v[18:33]
	v_mfma_f32_32x32x16_bf16 v[2:17], v[172:175], v[156:159], v[2:17]
	s_add_i32 s98, s80, 1
	s_cmp_lg_u32 s80, 2
	s_cselect_b32 s80, s98, 0
	s_add_u32 s22, s22, 0x80
	s_addc_u32 s23, s23, 0
	s_cmpk_eq_i32 s22, 0x1000
	s_cbranch_scc0 .LBB0_157
	s_setprio 0
	s_and_b64 vcc, exec, s[8:9]
	s_waitcnt lgkmcnt(0)
	s_barrier
	s_cbranch_vccz .LBB0_145
	s_lshl_b32 s6, s25, 8
	s_ashr_i32 s7, s6, 31
	s_lshl_b32 s8, s26, 7
	s_lshl_b64 s[6:7], s[6:7], 12
	s_add_u32 s22, s27, s6
	s_addc_u32 s23, s28, s7
	s_ashr_i32 s9, s8, 31
	s_lshl_b64 s[6:7], s[8:9], 12
	s_add_u32 s60, s30, s6
	s_addc_u32 s61, s31, s7
	s_add_u32 s6, s22, s20
	s_addc_u32 s7, s23, s21
	s_add_u32 s8, s22, s18
	s_addc_u32 s9, s23, s19
	s_add_u32 s16, s22, s16
	s_addc_u32 s17, s23, s17
	s_add_u32 s14, s22, s14
	s_mov_b32 m0, s59
	s_nop 0
	global_load_lds_dwordx4 v1, s[6:7]
	s_addc_u32 s15, s23, s15
	s_mov_b32 m0, s58
	s_nop 0
	global_load_lds_dwordx4 v1, s[8:9]
	s_add_u32 s12, s60, s12
	s_mov_b32 m0, s57
	s_nop 0
	global_load_lds_dwordx4 v1, s[16:17]
	s_addc_u32 s13, s61, s13
	s_add_i32 s18, s55, 0x4000
	s_mov_b32 m0, s56
	s_nop 0
	global_load_lds_dwordx4 v1, s[14:15]
	s_add_u32 s10, s60, s10
	s_mov_b32 m0, s18
	s_nop 0
	global_load_lds_dwordx4 v1, s[12:13]
	s_addc_u32 s11, s61, s11
	s_add_i32 s18, s54, 0x4000
	s_add_u32 s6, s6, 64
	s_mov_b32 m0, s18
	s_nop 0
	global_load_lds_dwordx4 v1, s[10:11]
	s_addc_u32 s7, s7, 0
	s_add_i32 s18, s59, 0x6000
	s_mov_b32 m0, s18
	s_nop 0
	global_load_lds_dwordx4 v1, s[6:7]
	s_add_u32 s6, s8, 64
	s_addc_u32 s7, s9, 0
	s_add_i32 s8, s58, 0x6000
	s_mov_b32 m0, s8
	s_nop 0
	global_load_lds_dwordx4 v1, s[6:7]
	s_add_u32 s6, s16, 64
	s_addc_u32 s7, s17, 0
	s_add_i32 s8, s57, 0x6000
	s_mov_b32 m0, s8
	s_nop 0
	global_load_lds_dwordx4 v1, s[6:7]
	s_add_u32 s6, s14, 64
	s_addc_u32 s7, s15, 0
	s_add_i32 s8, s56, 0x6000
	s_mov_b32 m0, s8
	s_nop 0
	global_load_lds_dwordx4 v1, s[6:7]
	s_add_u32 s6, s12, 64
	s_addc_u32 s7, s13, 0
	s_add_i32 s55, s55, 0xa000
	s_mov_b32 m0, s55
	s_nop 0
	global_load_lds_dwordx4 v1, s[6:7]
	s_add_u32 s6, s10, 64
	s_addc_u32 s7, s11, 0
	s_add_i32 s54, s54, 0xa000
	s_mov_b32 m0, s54
	s_nop 0
	global_load_lds_dwordx4 v1, s[6:7]
	s_branch .LBB0_145

; DEV void phase_attn(const Params& p, int l, char* lds) {
;     ...
;   while (true) {
;     __syncthreads();
;     if (threadIdx.x == 0) *slot = (int)__hip_atomic_fetch_add(ctr, 1u, __ATOMIC_RELAXED, __HIP_MEMORY_SCOPE_AGENT);
;     __syncthreads();
;     const int i0 = *slot;
.LBB0_166:
	s_setprio 0
	s_waitcnt lgkmcnt(0)
	s_barrier
	s_mov_b64 s[0:1], exec
	v_readlane_b32 s2, v239, 15
	v_readlane_b32 s3, v239, 16
	s_and_b64 s[2:3], s[0:1], s[2:3]
	s_mov_b64 exec, s[2:3]
	s_cbranch_execz .LBB0_168
	v_mov_b64_e32 v[2:3], s[42:43]
	flat_atomic_add v1, v[2:3], v196 sc0
	s_waitcnt vmcnt(0) lgkmcnt(0)
	ds_write_b32 v197, v1

; #define TOKQ ((size_t)b * SEQ + opq(qpos))
; template <int DQK, bool FOX>
; DEV void kv_dma(const bf16_t* __restrict__ Kg, int ldk, const bf16_t* __restrict__ Vtg, int ldv, const float* __restrict__ cumk,
;                 int key0, char* st, int w, int lane) {
;   const unsigned base = (unsigned)(size_t)st;
;   const bf16_t* kb = uni_ptr(Kg + (size_t)key0 * ldk);
;   const bf16_t* vb = uni_ptr(Vtg + key0);
;   if (DQK == 128) {
;     const int r0 = w * 16 + (lane >> 4);
;     const unsigned rowoff = (unsigned)r0 * (unsigned)ldk * 2u;
;     const unsigned pz0 = (unsigned)((lane & 15) ^ (lane >> 4));
; #pragma unroll
;     for (int c = 0; c < 4; ++c)
;       dma16s(kb + (size_t)(4 * c) * ldk, rowoff + ((pz0 ^ (unsigned)(4 * c)) << 4), __builtin_amdgcn_readfirstlane(base + (w * 4 + c) * 1024));
;   } else {
;     const int r0 = w * 16 + (lane >> 3);
; #pragma unroll
;     for (int c = 0; c < 2; ++c) {
;       const int row = r0 + 8 * c;
;       dma16s(kb, (unsigned)row * (unsigned)ldk * 2u + (unsigned)((((lane & 7) ^ ((row >> 1) & 7))) << 4), __builtin_amdgcn_readfirstlane(base + (w * 2 + c) * 1024));
;     }
;   }
;   {
;     const int d0 = w * 32 + (lane >> 3);
; #pragma unroll
;     for (int c = 0; c < 4; ++c) {
;       const int d = d0 + 8 * c;
;       dma16s(vb, (unsigned)d * (unsigned)ldv * 2u + (unsigned)((((lane & 7) ^ ((d >> 1) & 7))) << 4), __builtin_amdgcn_readfirstlane(base + 16384 + (w * 4 + c) * 1024));
;     }
;   }
;   if (FOX) { if (w == 0 && lane < 16) dma16s(uni_ptr(cumk + key0), (unsigned)lane * 16u, __builtin_amdgcn_readfirstlane(base + 32768)); }
; }
; DEV void nsa_item(const Params& p, int b, int tt, char* lds) {
;     ...
;   const int t0 = tt * 32, head = r32 >> 3, wq0 = t0 + 8 * w, qpos = wq0 + (r32 & 7);
;     ...
;   const float c2 = 0.08838834764831845f * LOG2E;
;   bf16x8 qf[8];
;   {
;     const bf16_t* qp = PR + TOKQ * PR_LD + PR_QA_RAW + head * 128 + hh * 8;
; #pragma unroll
;     for (int ks = 0; ks < 8; ++ks) qf[ks] = *(const bf16x8*)(qp + ks * 16);
;   }
;   const int cmaxq = (qpos - 31) >> 4;
.LBB0_196:
	s_setprio 3
	s_and_b32 s2, s64, 3
	s_lshl_b32 s3, s27, 2
	s_bfe_u32 s23, s64, 0x10002
	s_or_b32 s24, s3, s2
	v_mov_b32_e32 v1, v192
	s_mov_b64 s[80:81], s[70:71]
	s_barrier
	s_add_u32 s2, s80, 0x21bc8000
	v_ashrrev_i32_e32 v119, 6, v1
	s_addc_u32 s3, s81, 0
	s_lshl_b32 s22, s24, 5
	v_lshlrev_b32_e32 v124, 3, v119
	v_add_u32_e32 v129, s22, v124
	v_and_b32_e32 v125, 7, v1
	v_or_b32_e32 v128, v129, v125
	v_mov_b32_e32 v2, v128
	s_lshl_b32 s78, s23, 12
	s_mov_b32 s79, s29
	v_mov_b64_e32 v[4:5], s[2:3]
	v_ashrrev_i32_e32 v3, 31, v2
	v_lshl_add_u64 v[2:3], s[78:79], 0, v[2:3]
	v_bfe_u32 v138, v1, 3, 2
	v_mad_u64_u32 v[4:5], s[4:5], v2, s35, v[4:5]
	v_bfe_u32 v130, v1, 5, 1
	v_mad_i32_i24 v5, v3, s35, v5
	v_lshlrev_b32_e32 v2, 8, v138
	v_mov_b32_e32 v3, v0
	v_lshl_add_u64 v[2:3], v[4:5], 0, v[2:3]
	v_lshlrev_b32_e32 v122, 4, v130
	v_mov_b32_e32 v123, v0
	v_lshl_add_u64 v[2:3], v[2:3], 0, v[122:123]
	flat_load_dwordx4 v[82:85], v[2:3]
	flat_load_dwordx4 v[86:89], v[2:3] offset:32
	flat_load_dwordx4 v[90:93], v[2:3] offset:64
	flat_load_dwordx4 v[94:97], v[2:3] offset:96
	flat_load_dwordx4 v[98:101], v[2:3] offset:128
	flat_load_dwordx4 v[102:105], v[2:3] offset:160
	flat_load_dwordx4 v[106:109], v[2:3] offset:192
	flat_load_dwordx4 v[110:113], v[2:3] offset:224
	s_lshl_b32 s4, s23, 16
	s_add_u32 s6, s80, s4
	s_addc_u32 s7, s81, 0
	s_add_u32 s4, s6, 0x1fb68000
	s_addc_u32 s5, s7, 0
	s_add_u32 s14, s6, 0x1fb88000
	s_addc_u32 s15, s7, 0
	s_lshr_b32 s6, s27, 3
	v_mov_b32_e32 v2, v192
	s_add_i32 s6, s6, 1
	v_and_b32_e32 v121, 63, v1
	v_readfirstlane_b32 s8, v2
	v_and_b32_e32 v126, 31, v1
	v_subrev_u32_e32 v1, 31, v128
	s_lshl_b64 s[6:7], -1, s6
	s_ashr_i32 s10, s8, 6
	v_ashrrev_i32_e32 v127, 4, v1
	v_subrev_u32_e32 v1, 24, v129
	s_sub_u32 s8, 0x7e, s6
	v_ashrrev_i32_e32 v133, 4, v1
	s_subb_u32 s9, 0, s7
	v_bfe_u32 v1, v2, 4, 2
	s_andn2_b64 s[16:17], s[8:9], s[6:7]
	s_lshl_b32 s18, s10, 12
	v_lshlrev_b32_e32 v5, 8, v1
	v_bitop3_b32 v1, v1, v2, 15 bitop3:0x78
	v_lshl_or_b32 v5, v1, 4, v5
	s_add_u32 s6, s4, 0x400
	v_or_b32_e32 v1, s18, v5
	s_mov_b32 m0, s18
	s_nop 0
	global_load_lds_dwordx4 v1, s[4:5]
	s_addc_u32 s7, s5, 0
	s_add_i32 s8, s18, 0x400
	v_mov_b32_e32 v6, s18
	v_bitop3_b32 v22, v5, 64, s18 bitop3:0x36
	s_mov_b32 m0, s8
	s_nop 0
	global_load_lds_dwordx4 v22, s[6:7]
	s_add_u32 s6, s4, 0x800
	s_movk_i32 s8, 0x80
	s_addc_u32 s7, s5, 0
	v_bitop3_b32 v23, v5, s8, v6 bitop3:0x36
	s_add_i32 s8, s18, 0x800
	s_mov_b32 m0, s8
	s_nop 0
	global_load_lds_dwordx4 v23, s[6:7]
	s_add_u32 s6, s4, 0xc00
	s_addc_u32 s7, s5, 0
	s_movk_i32 s8, 0xc0
	v_and_b32_e32 v3, 63, v2
	v_bitop3_b32 v24, v5, s8, v6 bitop3:0x36
	s_add_i32 s8, s18, 0xc00
	s_mov_b32 m0, s8
	s_nop 0
	global_load_lds_dwordx4 v24, s[6:7]
	v_bfe_u32 v5, v2, 3, 3
	v_lshlrev_b32_e32 v6, 4, v2
	s_movk_i32 s7, 0x70
	v_lshl_or_b32 v5, s10, 5, v5
	v_bitop3_b32 v3, v6, s7, v3 bitop3:0x48
	v_lshl_or_b32 v25, v5, 9, v3
	v_or_b32_e32 v3, 8, v5
	v_lshlrev_b32_e32 v6, 9, v3
	v_lshrrev_b32_e32 v3, 1, v3
	v_xor_b32_e32 v3, v3, v2
	v_lshlrev_b32_e32 v3, 4, v3
	v_and_or_b32 v26, v3, s7, v6
	v_or_b32_e32 v3, 24, v5
	v_lshlrev_b32_e32 v5, 9, v3
	v_lshrrev_b32_e32 v3, 1, v3
	v_xor_b32_e32 v3, v3, v2
	v_lshlrev_b32_e32 v3, 4, v3
	v_bfe_u32 v4, v2, 5, 1
	v_and_or_b32 v28, v3, s7, v5
	v_and_b32_e32 v3, 19, v2
	v_lshlrev_b32_e32 v5, 1, v2
	v_lshrrev_b32_e32 v2, 1, v2
	v_and_b32_e32 v5, 8, v5
	v_and_b32_e32 v2, 4, v2
	v_or3_b32 v2, v5, v3, v2
	v_bitop3_b32 v3, v2, v4, 15 bitop3:0x6c
	v_lshlrev_b32_e32 v30, 4, v3
	v_or_b32_e32 v3, 2, v4
	v_bitop3_b32 v3, v2, v3, 15 bitop3:0x6c
	v_lshlrev_b32_e32 v31, 4, v3
	v_or_b32_e32 v3, 4, v4
	v_bitop3_b32 v3, v2, v3, 15 bitop3:0x6c
	v_lshlrev_b32_e32 v32, 4, v3
	v_or_b32_e32 v3, 6, v4
	v_bitop3_b32 v3, v2, v3, 15 bitop3:0x6c
	v_lshlrev_b32_e32 v33, 4, v3
	v_or_b32_e32 v3, 8, v4
	v_bitop3_b32 v3, v2, v3, 15 bitop3:0x6c
	v_lshlrev_b32_e32 v34, 4, v3
	v_or_b32_e32 v3, 10, v4
	s_add_i32 s6, s18, 0x4000
	s_mov_b32 m0, s6
	s_nop 0
	global_load_lds_dwordx4 v25, s[14:15]
	v_bitop3_b32 v3, v2, v3, 15 bitop3:0x6c
	s_add_i32 s6, s18, 0x4400
	s_mov_b32 m0, s6
	s_nop 0
	global_load_lds_dwordx4 v26, s[14:15]
	v_lshlrev_b32_e32 v35, 4, v3
	v_or_b32_e32 v3, 12, v4
	v_or_b32_e32 v27, 0x2000, v25
	s_add_i32 s6, s18, 0x4800
	s_mov_b32 m0, s6
	s_nop 0
	global_load_lds_dwordx4 v27, s[14:15]
	v_bitop3_b32 v3, v2, v3, 15 bitop3:0x6c
	s_add_i32 s6, s18, 0x4c00
	s_mov_b32 m0, s6
	s_nop 0
	global_load_lds_dwordx4 v28, s[14:15]
	v_lshlrev_b32_e32 v36, 4, v3
	v_or_b32_e32 v3, 14, v4
	v_lshlrev_b32_e32 v29, 8, v2
	v_bitop3_b32 v2, v2, v3, 15 bitop3:0x6c
	v_lshlrev_b32_e32 v118, 7, v138
	v_lshlrev_b32_e32 v120, 3, v130
	v_lshlrev_b32_e32 v37, 4, v2
	v_lshlrev_b32_e32 v38, 3, v4
	s_mov_b64 s[6:7], 0
	s_mov_b32 s19, 0
	v_mov_b32_e32 v47, 0
	v_mov_b32_e32 v141, 0xe0ad78ec
	s_mov_b64 s[8:9], s[16:17]

; DEV f32x16 mfma(bf16x8 a, bf16x8 b, f32x16 c) { return __builtin_amdgcn_mfma_f32_32x32x16_bf16(a, b, c, 0, 0, 0); }
;     ...
;   for (int kt = 0; kt < nk; ++kt) {
;     if (kt + 1 < nk) { if (MI == 4) asm volatile("s_waitcnt vmcnt(6)" ::: "memory"); else asm volatile("s_waitcnt vmcnt(4)" ::: "memory"); } else asm volatile("s_waitcnt vmcnt(0)" ::: "memory");
;     __builtin_amdgcn_s_barrier();
;     if (kt + 2 < nk) { int s2 = stg + 2; if (s2 >= 3) s2 -= 3; g2_issue<MI>(ag + (size_t)(kt + 2) * 32, bg + (size_t)(kt + 2) * 32, lda, ldb, voffa, voffb, lds + s2 * G2_STAGE, w); }
;     const unsigned so = (unsigned)(stg * G2_STAGE);
;     __builtin_amdgcn_s_setprio(1);
; #pragma unroll
;     for (int ks = 0; ks < 2; ++ks) {
;       const unsigned aa = (ks ? la1 : la0) + so, bb = (ks ? lb1 : lb0) + so;
;       bf16x8 fb0, fb1, fa0, fa1, fa2, fa3;
;       asm volatile("ds_read_b128 %0, %1" : "=v"(fb0) : "v"(bb));
;       asm volatile("ds_read_b128 %0, %1 offset:2048" : "=v"(fb1) : "v"(bb));
;       asm volatile("ds_read_b128 %0, %1" : "=v"(fa0) : "v"(aa));
;       asm volatile("ds_read_b128 %0, %1 offset:2048" : "=v"(fa1) : "v"(aa));
;       if constexpr (MI == 4) {
;         asm volatile("ds_read_b128 %0, %1 offset:4096" : "=v"(fa2) : "v"(aa));
;         asm volatile("ds_read_b128 %0, %1 offset:6144" : "=v"(fa3) : "v"(aa));
;         __builtin_amdgcn_sched_barrier(0);
;         asm volatile("s_waitcnt lgkmcnt(3)" : "+v"(fb0), "+v"(fb1), "+v"(fa0));
;         acc[0][0][0] = mfma(fa0, fb0, acc[0][0][0]); acc[0][0][1] = mfma(fa0, fb1, acc[0][0][1]); __builtin_amdgcn_sched_barrier(0);
;         asm volatile("s_waitcnt lgkmcnt(2)" : "+v"(fa1));
;         acc[0][1][0] = mfma(fa1, fb0, acc[0][1][0]); acc[0][1][1] = mfma(fa1, fb1, acc[0][1][1]); __builtin_amdgcn_sched_barrier(0);
;         asm volatile("s_waitcnt lgkmcnt(1)" : "+v"(fa2));
;         acc[MI / 2 - 1][0][0] = mfma(fa2, fb0, acc[MI / 2 - 1][0][0]); acc[MI / 2 - 1][0][1] = mfma(fa2, fb1, acc[MI / 2 - 1][0][1]); __builtin_amdgcn_sched_barrier(0);
;         asm volatile("s_waitcnt lgkmcnt(0)" : "+v"(fa3));
;         acc[MI / 2 - 1][1][0] = mfma(fa3, fb0, acc[MI / 2 - 1][1][0]); acc[MI / 2 - 1][1][1] = mfma(fa3, fb1, acc[MI / 2 - 1][1][1]); __builtin_amdgcn_sched_barrier(0);
;       } else {
;         __builtin_amdgcn_sched_barrier(0);
;         asm volatile("s_waitcnt lgkmcnt(1)" : "+v"(fb0), "+v"(fb1), "+v"(fa0));
.Lhy2_issue_out:
	s_mul_i32 s99, s79, 0x6000
	s_setprio 1
	v_add_u32_e32 v153, s99, v138
	v_add_u32_e32 v178, s99, v141
	v_add_u32_e32 v174, v153, v147
	v_add_u32_e32 v158, v178, v147
	ds_read_b128 v[154:157], v158
	ds_read_b128 v[158:161], v158 offset:2048
	ds_read_b128 v[162:165], v174
	ds_read_b128 v[166:169], v174 offset:2048
	ds_read_b128 v[170:173], v174 offset:4096
	ds_read_b128 v[174:177], v174 offset:6144
	s_cmpk_eq_i32 s18, 0xf80
	s_cbranch_scc1 .Lhy2_noissue_out
	s_nop 0
	s_waitcnt lgkmcnt(3)
	s_nop 0
	v_mfma_f32_32x32x16_bf16 v[114:129], v[162:165], v[154:157], v[114:129]
	v_mfma_f32_32x32x16_bf16 v[98:113], v[162:165], v[158:161], v[98:113]
	s_mov_b32 m0, s83
	s_nop 0
	global_load_lds_dwordx4 v1, s[80:81]
	global_load_dwordx4 v[214:217], v1, s[80:81] offset:64
	s_add_u32 s80, s74, s18
	s_addc_u32 s81, s75, s19
	s_add_i32 s83, s26, s82
	s_mov_b32 m0, s83
	s_nop 0
	global_load_lds_dwordx4 v1, s[80:81]
	global_load_dwordx4 v[218:221], v1, s[80:81] offset:64
	s_waitcnt lgkmcnt(2)
	s_nop 0
	v_mfma_f32_32x32x16_bf16 v[82:97], v[166:169], v[154:157], v[82:97]
	v_mfma_f32_32x32x16_bf16 v[66:81], v[166:169], v[158:161], v[66:81]
	s_add_u32 s80, s59, s18
	s_addc_u32 s81, s63, s19
	s_add_i32 s83, s27, s82
	s_mov_b32 m0, s83
	s_nop 0
	global_load_lds_dwordx4 v1, s[80:81]
	global_load_dwordx4 v[222:225], v1, s[80:81] offset:64
	s_add_u32 s80, s57, s18
	s_addc_u32 s81, s58, s19
	s_add_i32 s83, s28, s82
	s_addk_i32 s82, 0x4000
	s_mov_b32 m0, s83
	s_nop 0
	global_load_lds_dwordx4 v1, s[80:81]
	global_load_dwordx4 v[226:229], v1, s[80:81] offset:64
	s_waitcnt lgkmcnt(1)
	s_nop 0
	v_mfma_f32_32x32x16_bf16 v[50:65], v[170:173], v[154:157], v[50:65]
	v_mfma_f32_32x32x16_bf16 v[34:49], v[170:173], v[158:161], v[34:49]
	s_add_u32 s80, s20, s18
	s_addc_u32 s81, s21, s19
	s_add_i32 s83, s82, s30
	s_mov_b32 m0, s83
	s_nop 0
	global_load_lds_dwordx4 v1, s[80:81]
	global_load_dwordx4 v[230:233], v1, s[80:81] offset:64
	s_add_u32 s80, s6, s18
	s_addc_u32 s81, s7, s19
	s_add_i32 s82, s82, s31
	s_mov_b32 m0, s82
	s_nop 0
	global_load_lds_dwordx4 v1, s[80:81]
	global_load_dwordx4 v[234:237], v1, s[80:81] offset:64
	s_waitcnt lgkmcnt(0)
	s_nop 0
	v_mfma_f32_32x32x16_bf16 v[18:33], v[174:177], v[154:157], v[18:33]
	v_mfma_f32_32x32x16_bf16 v[2:17], v[174:177], v[158:161], v[2:17]
	s_branch .Lhy2_after_out
.Lhy2_noissue_out:
	s_nop 0
	s_waitcnt lgkmcnt(3)
	s_nop 0
	v_mfma_f32_32x32x16_bf16 v[114:129], v[162:165], v[154:157], v[114:129]
	v_mfma_f32_32x32x16_bf16 v[98:113], v[162:165], v[158:161], v[98:113]
	s_waitcnt lgkmcnt(2)
	s_nop 0
	v_mfma_f32_32x32x16_bf16 v[82:97], v[166:169], v[154:157], v[82:97]
	v_mfma_f32_32x32x16_bf16 v[66:81], v[166:169], v[158:161], v[66:81]
	s_waitcnt lgkmcnt(1)
	s_nop 0
	v_mfma_f32_32x32x16_bf16 v[50:65], v[170:173], v[154:157], v[50:65]
	v_mfma_f32_32x32x16_bf16 v[34:49], v[170:173], v[158:161], v[34:49]
	s_waitcnt lgkmcnt(0)
	s_nop 0
	v_mfma_f32_32x32x16_bf16 v[18:33], v[174:177], v[154:157], v[18:33]
	v_mfma_f32_32x32x16_bf16 v[2:17], v[174:177], v[158:161], v[2:17]
; DEV f32x16 mfma(bf16x8 a, bf16x8 b, f32x16 c) { return __builtin_amdgcn_mfma_f32_32x32x16_bf16(a, b, c, 0, 0, 0); }
;     ...
;   for (int kt = 0; kt < nk; ++kt) {
;     if (kt + 1 < nk) { if (MI == 4) asm volatile("s_waitcnt vmcnt(6)" ::: "memory"); else asm volatile("s_waitcnt vmcnt(4)" ::: "memory"); } else asm volatile("s_waitcnt vmcnt(0)" ::: "memory");
;     __builtin_amdgcn_s_barrier();
;     if (kt + 2 < nk) { int s2 = stg + 2; if (s2 >= 3) s2 -= 3; g2_issue<MI>(ag + (size_t)(kt + 2) * 32, bg + (size_t)(kt + 2) * 32, lda, ldb, voffa, voffb, lds + s2 * G2_STAGE, w); }
;     const unsigned so = (unsigned)(stg * G2_STAGE);
;     __builtin_amdgcn_s_setprio(1);
; #pragma unroll
;     for (int ks = 0; ks < 2; ++ks) {
;       const unsigned aa = (ks ? la1 : la0) + so, bb = (ks ? lb1 : lb0) + so;
;       bf16x8 fb0, fb1, fa0, fa1, fa2, fa3;
;       asm volatile("ds_read_b128 %0, %1" : "=v"(fb0) : "v"(bb));
;       asm volatile("ds_read_b128 %0, %1 offset:2048" : "=v"(fb1) : "v"(bb));
;       asm volatile("ds_read_b128 %0, %1" : "=v"(fa0) : "v"(aa));
;       asm volatile("ds_read_b128 %0, %1 offset:2048" : "=v"(fa1) : "v"(aa));
;       if constexpr (MI == 4) {
;         asm volatile("ds_read_b128 %0, %1 offset:4096" : "=v"(fa2) : "v"(aa));
;         asm volatile("ds_read_b128 %0, %1 offset:6144" : "=v"(fa3) : "v"(aa));
;         __builtin_amdgcn_sched_barrier(0);
;         asm volatile("s_waitcnt lgkmcnt(3)" : "+v"(fb0), "+v"(fb1), "+v"(fa0));
;         acc[0][0][0] = mfma(fa0, fb0, acc[0][0][0]); acc[0][0][1] = mfma(fa0, fb1, acc[0][0][1]); __builtin_amdgcn_sched_barrier(0);
;         asm volatile("s_waitcnt lgkmcnt(2)" : "+v"(fa1));
;         acc[0][1][0] = mfma(fa1, fb0, acc[0][1][0]); acc[0][1][1] = mfma(fa1, fb1, acc[0][1][1]); __builtin_amdgcn_sched_barrier(0);
;         asm volatile("s_waitcnt lgkmcnt(1)" : "+v"(fa2));
;         acc[MI / 2 - 1][0][0] = mfma(fa2, fb0, acc[MI / 2 - 1][0][0]); acc[MI / 2 - 1][0][1] = mfma(fa2, fb1, acc[MI / 2 - 1][0][1]); __builtin_amdgcn_sched_barrier(0);
;         asm volatile("s_waitcnt lgkmcnt(0)" : "+v"(fa3));
;         acc[MI / 2 - 1][1][0] = mfma(fa3, fb0, acc[MI / 2 - 1][1][0]); acc[MI / 2 - 1][1][1] = mfma(fa3, fb1, acc[MI / 2 - 1][1][1]); __builtin_amdgcn_sched_barrier(0);
;       } else {
;         __builtin_amdgcn_sched_barrier(0);
;         asm volatile("s_waitcnt lgkmcnt(1)" : "+v"(fb0), "+v"(fb1), "+v"(fa0));
.Lhy2_after_out:
	v_add_u32_e32 v158, v178, v145
	v_add_u32_e32 v153, v153, v145
	ds_read_b128 v[154:157], v158
	ds_read_b128 v[158:161], v158 offset:2048
	ds_read_b128 v[162:165], v153
	ds_read_b128 v[166:169], v153 offset:2048
	ds_read_b128 v[170:173], v153 offset:4096
	ds_read_b128 v[174:177], v153 offset:6144
	s_nop 0
	s_waitcnt lgkmcnt(3)
	s_nop 0
	v_mfma_f32_32x32x16_bf16 v[114:129], v[162:165], v[154:157], v[114:129]
	v_mfma_f32_32x32x16_bf16 v[98:113], v[162:165], v[158:161], v[98:113]
	s_waitcnt lgkmcnt(2)
	s_nop 0
	v_mfma_f32_32x32x16_bf16 v[82:97], v[166:169], v[154:157], v[82:97]
	v_mfma_f32_32x32x16_bf16 v[66:81], v[166:169], v[158:161], v[66:81]
	s_waitcnt lgkmcnt(1)
	s_nop 0
	v_mfma_f32_32x32x16_bf16 v[50:65], v[170:173], v[154:157], v[50:65]
	v_mfma_f32_32x32x16_bf16 v[34:49], v[170:173], v[158:161], v[34:49]
	s_waitcnt lgkmcnt(0)
	s_nop 0
	v_mfma_f32_32x32x16_bf16 v[18:33], v[174:177], v[154:157], v[18:33]
	v_mfma_f32_32x32x16_bf16 v[2:17], v[174:177], v[158:161], v[2:17]
	s_setprio 0
	s_add_i32 s98, s79, 1
	s_cmp_lg_u32 s79, 2
	s_cselect_b32 s79, s98, 0
	s_waitcnt vmcnt(12)
	s_barrier
	s_mul_i32 s80, s79, 0x6000
	s_setprio 1
	v_add_u32_e32 v153, s80, v138
	v_add_u32_e32 v178, s80, v141
	v_add_u32_e32 v174, v153, v147
	v_add_u32_e32 v158, v178, v147
	ds_read_b128 v[154:157], v158
	ds_read_b128 v[158:161], v158 offset:2048
	ds_read_b128 v[162:165], v174
	ds_read_b128 v[166:169], v174 offset:2048
	ds_read_b128 v[170:173], v174 offset:4096
	ds_read_b128 v[174:177], v174 offset:6144
	s_nop 0
	s_waitcnt lgkmcnt(3)
	s_nop 0
	v_mfma_f32_32x32x16_bf16 v[114:129], v[162:165], v[154:157], v[114:129]
	v_mfma_f32_32x32x16_bf16 v[98:113], v[162:165], v[158:161], v[98:113]
	s_waitcnt lgkmcnt(2)
	s_nop 0
	v_mfma_f32_32x32x16_bf16 v[82:97], v[166:169], v[154:157], v[82:97]
	v_mfma_f32_32x32x16_bf16 v[66:81], v[166:169], v[158:161], v[66:81]
	s_waitcnt lgkmcnt(1)
	s_nop 0
	v_mfma_f32_32x32x16_bf16 v[50:65], v[170:173], v[154:157], v[50:65]
	v_mfma_f32_32x32x16_bf16 v[34:49], v[170:173], v[158:161], v[34:49]
	s_waitcnt lgkmcnt(0)
	s_nop 0
	v_mfma_f32_32x32x16_bf16 v[18:33], v[174:177], v[154:157], v[18:33]
	v_mfma_f32_32x32x16_bf16 v[2:17], v[174:177], v[158:161], v[2:17]
	v_add_u32_e32 v158, v178, v145
	v_add_u32_e32 v153, v153, v145
	ds_read_b128 v[154:157], v158
	ds_read_b128 v[158:161], v158 offset:2048
	ds_read_b128 v[162:165], v153
	ds_read_b128 v[166:169], v153 offset:2048
	ds_read_b128 v[170:173], v153 offset:4096
	ds_read_b128 v[174:177], v153 offset:6144
	s_nop 0
	s_waitcnt lgkmcnt(3)
	s_nop 0
	v_mfma_f32_32x32x16_bf16 v[114:129], v[162:165], v[154:157], v[114:129]
	v_mfma_f32_32x32x16_bf16 v[98:113], v[162:165], v[158:161], v[98:113]
	s_waitcnt lgkmcnt(2)
	s_nop 0
	v_mfma_f32_32x32x16_bf16 v[82:97], v[166:169], v[154:157], v[82:97]
	v_mfma_f32_32x32x16_bf16 v[66:81], v[166:169], v[158:161], v[66:81]
	s_waitcnt lgkmcnt(1)
	s_nop 0
	v_mfma_f32_32x32x16_bf16 v[50:65], v[170:173], v[154:157], v[50:65]
	v_mfma_f32_32x32x16_bf16 v[34:49], v[170:173], v[158:161], v[34:49]
	s_waitcnt lgkmcnt(0)
	s_nop 0
	v_mfma_f32_32x32x16_bf16 v[18:33], v[174:177], v[154:157], v[18:33]
	v_mfma_f32_32x32x16_bf16 v[2:17], v[174:177], v[158:161], v[2:17]
	s_add_i32 s98, s79, 1
	s_cmp_lg_u32 s79, 2
	s_cselect_b32 s79, s98, 0
	s_add_u32 s18, s18, 0x80
	s_addc_u32 s19, s19, 0
	s_cmpk_eq_i32 s18, 0x1000
	s_cbranch_scc0 .LBB0_537
	s_setprio 0
	s_and_b64 vcc, exec, s[2:3]
	s_waitcnt lgkmcnt(0)
	s_barrier
	s_cbranch_vccz .LBB0_540
	s_lshl_b32 s2, s53, 8
	s_ashr_i32 s3, s2, 31
	s_lshl_b32 s6, s54, 7
	s_lshl_b64 s[2:3], s[2:3], 12
	s_add_u32 s18, s24, s2
	s_addc_u32 s19, s25, s3
	s_ashr_i32 s7, s6, 31
	s_lshl_b64 s[2:3], s[6:7], 12
	s_add_u32 s20, s22, s2
	s_addc_u32 s21, s23, s3
	s_add_u32 s2, s18, s16
	s_addc_u32 s3, s19, s17
	s_add_u32 s6, s18, s14
	s_addc_u32 s7, s19, s15
	s_add_u32 s12, s18, s12
	s_addc_u32 s13, s19, s13
	s_add_u32 s10, s18, s10
	s_mov_b32 m0, s1
	s_nop 0
	global_load_lds_dwordx4 v1, s[2:3]
	s_addc_u32 s11, s19, s11
	s_mov_b32 m0, s26
	s_nop 0
	global_load_lds_dwordx4 v1, s[6:7]
	s_add_u32 s8, s20, s8
	s_mov_b32 m0, s27
	s_nop 0
	global_load_lds_dwordx4 v1, s[12:13]
	s_addc_u32 s9, s21, s9
	s_add_i32 s14, s30, 0x4000
	s_mov_b32 m0, s28
	s_nop 0
	global_load_lds_dwordx4 v1, s[10:11]
	s_add_u32 s4, s20, s4
	s_mov_b32 m0, s14
	s_nop 0
	global_load_lds_dwordx4 v1, s[8:9]
	s_addc_u32 s5, s21, s5
	s_add_i32 s14, s31, 0x4000
	s_add_u32 s2, s2, 64
	s_mov_b32 m0, s14
	s_nop 0
	global_load_lds_dwordx4 v1, s[4:5]
	s_addc_u32 s3, s3, 0
	s_addk_i32 s1, 0x6000
	s_mov_b32 m0, s1
	s_nop 0
	global_load_lds_dwordx4 v1, s[2:3]
	s_add_u32 s2, s6, 64
	s_addc_u32 s3, s7, 0
	s_add_i32 s1, s26, 0x6000
	s_mov_b32 m0, s1
	s_nop 0
	global_load_lds_dwordx4 v1, s[2:3]
	s_add_u32 s2, s12, 64
	s_addc_u32 s3, s13, 0
	s_add_i32 s1, s27, 0x6000
	s_mov_b32 m0, s1
	s_nop 0
	global_load_lds_dwordx4 v1, s[2:3]
	s_add_u32 s2, s10, 64
	s_addc_u32 s3, s11, 0
	s_add_i32 s1, s28, 0x6000
	s_mov_b32 m0, s1
	s_nop 0
	global_load_lds_dwordx4 v1, s[2:3]
	s_add_u32 s2, s8, 64
	s_addc_u32 s3, s9, 0
	s_add_i32 s1, s30, 0xa000
	s_mov_b32 m0, s1
	s_nop 0
	global_load_lds_dwordx4 v1, s[2:3]
	s_add_u32 s2, s4, 64
	s_addc_u32 s3, s5, 0
	s_add_i32 s1, s31, 0xa000
	s_mov_b32 m0, s1
	s_nop 0
	global_load_lds_dwordx4 v1, s[2:3]

; DEV char* wsp(const Params& p) { char* w = p.ws; asm volatile("" : "+s"(w)); return w; }
; DEV void rowwise_row(int row, int lane, const bf16_t* __restrict__ add, const float* __restrict__ gpost, const float* __restrict__ xin,
;                      float* __restrict__ xout, const float* __restrict__ gpre, bf16_t* __restrict__ hin, float* __restrict__ fout) {
;   float4 xv[8];
;   const size_t base = (size_t)row * DM;
; #pragma unroll
;   for (int j = 0; j < 8; ++j) xv[j] = *(const float4*)(xin + base + j * 256 + lane * 4);
;   if (add) {
;     float4 av[8]; float ss = 0.f;
; #pragma unroll
;     for (int j = 0; j < 8; ++j) {
;       uint2 u = *(const uint2*)(add + base + j * 256 + lane * 4);
;       av[j] = make_float4(bf2f(u.x & 0xffffu), bf2f(u.x >> 16), bf2f(u.y & 0xffffu), bf2f(u.y >> 16));
;       ss += av[j].x * av[j].x + av[j].y * av[j].y + av[j].z * av[j].z + av[j].w * av[j].w;
;     }
;     ss = wave_sum(ss);
;     float rs = rsqrtf(ss * (1.f / DM) + EPS);
; #pragma unroll
;     for (int j = 0; j < 8; ++j) {
;       float4 g = *(const float4*)(gpost + j * 256 + lane * 4);
;       xv[j].x += av[j].x * rs * g.x; xv[j].y += av[j].y * rs * g.y; xv[j].z += av[j].z * rs * g.z; xv[j].w += av[j].w * rs * g.w;
;     }
;   }
;   if (xout) {
; #pragma unroll
;     for (int j = 0; j < 8; ++j) *(float4*)(xout + base + j * 256 + lane * 4) = xv[j];
;   }
;   if (fout) {
; #pragma unroll
;     for (int j = 0; j < 8; ++j) *(float4*)(fout + base + j * 256 + lane * 4) = xv[j];
;   }
;   if (gpre) {
;     float ss = 0.f;
; #pragma unroll
;     for (int j = 0; j < 8; ++j) ss += xv[j].x * xv[j].x + xv[j].y * xv[j].y + xv[j].z * xv[j].z + xv[j].w * xv[j].w;
;     ss = wave_sum(ss);
;     float rs = rsqrtf(ss * (1.f / DM) + EPS);
; #pragma unroll
;     for (int j = 0; j < 8; ++j) {
;       float4 g = *(const float4*)(gpre + j * 256 + lane * 4);
;       uint2 o; o.x = cvtpk(xv[j].x * rs * g.x, xv[j].y * rs * g.y); o.y = cvtpk(xv[j].z * rs * g.z, xv[j].w * rs * g.w);
;       *(uint2*)(hin + base + j * 256 + lane * 4) = o;
; DEV void phase_prep(const Params& p, char* lds) {
;     ...
;     } else if (it < n_tr + n_rope + n_pec + n_row) {
;       int row = (it - n_tr - n_rope - n_pec) * 4 + (tid >> 6);
;       rowwise_row(row, tid & 63, nullptr, nullptr, p.x_in, (float*)(wsp(p) + OFF_X), p.g_mix_pre, (bf16_t*)(wsp(p) + OFF_HIN), nullptr);
.LBB0_1883:
	s_cmp_gt_i32 s20, 0xcaff
	s_mov_b64 s[0:1], -1
	s_cbranch_scc0 .LBB0_1908
	s_cmpk_gt_u32 s20, 0xcc7f
	s_cbranch_scc0 .LBB0_1901
	s_cmpk_gt_u32 s20, 0xccff
	s_cbranch_scc0 .LBB0_1896
	s_cmpk_lg_u32 s20, 0xd500
	s_cbranch_scc0 .LBB0_1890
	v_lshl_add_u32 v54, s20, 2, v1
	v_ashrrev_i32_e32 v55, 31, v54
	v_lshlrev_b64 v[56:57], 13, v[54:55]
	s_mov_b64 s[2:3], s[70:71]
	s_mov_b64 s[0:1], s[70:71]
	v_lshl_add_u64 v[2:3], v[38:39], 0, v[56:57]
	global_load_dwordx4 v[30:33], v[2:3], off
	global_load_dwordx4 v[26:29], v[2:3], off offset:1024
	global_load_dwordx4 v[22:25], v[2:3], off offset:2048
	global_load_dwordx4 v[18:21], v[2:3], off offset:3072
	v_add_co_u32_e32 v2, vcc, 0x1000, v2
	v_lshl_add_u64 v[56:57], s[2:3], 0, v[56:57]
	s_nop 0
	v_addc_co_u32_e32 v3, vcc, 0, v3, vcc
	global_load_dwordx4 v[14:17], v[2:3], off
	global_load_dwordx4 v[10:13], v[2:3], off offset:1024
	global_load_dwordx4 v[6:9], v[2:3], off offset:2048
	s_nop 0
	global_load_dwordx4 v[2:5], v[2:3], off offset:3072
	v_lshlrev_b32_e32 v62, 2, v36
	v_mov_b32_e32 v63, v0
	v_lshl_add_u64 v[56:57], v[56:57], 0, v[62:63]
	s_mov_b64 s[2:3], 0x196e0000
	v_lshl_add_u64 v[62:63], v[56:57], 0, s[2:3]
	s_mov_b32 s2, 0x196e0000
	v_add_co_u32_e32 v64, vcc, s2, v56
	v_readlane_b32 s2, v240, 46
	s_nop 0
	v_addc_co_u32_e32 v65, vcc, 0, v57, vcc
	v_add_co_u32_e32 v56, vcc, 0x196e1000, v56
	v_readlane_b32 s3, v240, 47
	s_nop 0
	v_addc_co_u32_e32 v57, vcc, 0, v57, vcc
	s_andn2_b64 vcc, exec, s[2:3]
	s_waitcnt vmcnt(0)
	flat_store_dwordx4 v[64:65], v[30:33]
	flat_store_dwordx4 v[62:63], v[26:29] offset:1024
	flat_store_dwordx4 v[62:63], v[22:25] offset:2048
	flat_store_dwordx4 v[62:63], v[18:21] offset:3072
	flat_store_dwordx4 v[56:57], v[14:17]
	flat_store_dwordx4 v[56:57], v[10:13] offset:1024
	flat_store_dwordx4 v[56:57], v[6:9] offset:2048
	flat_store_dwordx4 v[56:57], v[2:5] offset:3072
	s_cbranch_vccnz .LBB0_1889
	v_lshlrev_b64 v[56:57], 11, v[54:55]
	v_pk_mul_f32 v[54:55], v[30:31], v[30:31]
	v_pk_mul_f32 v[62:63], v[32:33], v[32:33]
	v_pk_mul_f32 v[64:65], v[26:27], v[26:27]
	v_add_f32_e32 v54, v54, v55
	v_pk_mul_f32 v[66:67], v[28:29], v[28:29]
	v_add_f32_e32 v35, v64, v65
	v_add_f32_e32 v54, v54, v62
	v_add_f32_e32 v35, v35, v66
	v_add_f32_e32 v54, v54, v63
	v_lshl_add_u64 v[56:57], v[56:57], 1, s[0:1]
	v_lshlrev_b32_e32 v62, 1, v36
	v_mov_b32_e32 v63, v0
	v_add_f32_e32 v35, v35, v67
	v_lshl_add_u64 v[66:67], v[56:57], 0, v[62:63]
	global_load_dwordx4 v[62:65], v[40:41], off
	global_load_dwordx4 v[178:181], v[40:41], off offset:1024
	global_load_dwordx4 v[182:185], v[40:41], off offset:2048
	global_load_dwordx4 v[186:189], v[40:41], off offset:3072
	global_load_dwordx4 v[214:217], v[42:43], off
	global_load_dwordx4 v[218:221], v[44:45], off
	global_load_dwordx4 v[222:225], v[46:47], off
	global_load_dwordx4 v[226:229], v[48:49], off
	v_pk_mul_f32 v[68:69], v[22:23], v[22:23]
	v_pk_mul_f32 v[70:71], v[24:25], v[24:25]
	v_add_f32_e32 v35, v54, v35
	v_add_f32_e32 v54, v68, v69
	v_mov_b32_e32 v78, v15
	v_mov_b32_e32 v79, v11
	v_add_f32_e32 v54, v54, v70
	v_pk_mul_f32 v[72:73], v[18:19], v[18:19]
	v_mov_b32_e32 v76, v14
	v_mov_b32_e32 v77, v10
	v_pk_mul_f32 v[78:79], v[78:79], v[78:79]
	v_add_f32_e32 v54, v54, v71
	v_pk_mul_f32 v[74:75], v[20:21], v[20:21]
	v_pk_fma_f32 v[76:77], v[76:77], v[76:77], v[78:79]
	v_mov_b32_e32 v78, v16
	v_mov_b32_e32 v79, v12
	v_add_f32_e32 v35, v35, v54
	v_add_f32_e32 v54, v72, v73
	v_pk_fma_f32 v[76:77], v[78:79], v[78:79], v[76:77]
	v_mov_b32_e32 v78, v17
	v_mov_b32_e32 v79, v13
	v_mov_b32_e32 v80, v7
	v_mov_b32_e32 v81, v3
	v_add_f32_e32 v54, v54, v74
	v_pk_fma_f32 v[76:77], v[78:79], v[78:79], v[76:77]
	v_mov_b32_e32 v78, v6
	v_mov_b32_e32 v79, v2
	v_pk_mul_f32 v[80:81], v[80:81], v[80:81]
	v_add_f32_e32 v54, v54, v75
	v_pk_fma_f32 v[78:79], v[78:79], v[78:79], v[80:81]
	v_mov_b32_e32 v80, v8
	v_mov_b32_e32 v81, v4
	v_add_f32_e32 v35, v35, v54
	v_pk_fma_f32 v[78:79], v[80:81], v[80:81], v[78:79]
	v_mov_b32_e32 v80, v9
	v_mov_b32_e32 v81, v5
	v_add_f32_e32 v35, v35, v76
	v_pk_fma_f32 v[78:79], v[80:81], v[80:81], v[78:79]
	v_add_f32_e32 v35, v35, v77
	v_cmp_lt_i32_e32 vcc, v203, v202
	v_add_f32_e32 v35, v35, v78
	v_add_f32_e32 v35, v35, v79
	v_cndmask_b32_e32 v54, v200, v203, vcc
	v_lshlrev_b32_e32 v54, 2, v54
	ds_bpermute_b32 v54, v54, v35
	v_cmp_lt_i32_e32 vcc, v204, v202
	s_mov_b64 s[0:1], 0x1d6e0000
	v_lshl_add_u64 v[56:57], v[66:67], 0, s[0:1]
	s_mov_b32 s0, 0x1d6e0000
	s_waitcnt lgkmcnt(0)
; DEV void rowwise_row(int row, int lane, const bf16_t* __restrict__ add, const float* __restrict__ gpost, const float* __restrict__ xin,
;                      float* __restrict__ xout, const float* __restrict__ gpre, bf16_t* __restrict__ hin, float* __restrict__ fout) {
;     ...
;   if (gpre) {
;     float ss = 0.f;
; #pragma unroll
;     for (int j = 0; j < 8; ++j) ss += xv[j].x * xv[j].x + xv[j].y * xv[j].y + xv[j].z * xv[j].z + xv[j].w * xv[j].w;
;     ss = wave_sum(ss);
;     float rs = rsqrtf(ss * (1.f / DM) + EPS);
; #pragma unroll
;     for (int j = 0; j < 8; ++j) {
;       float4 g = *(const float4*)(gpre + j * 256 + lane * 4);
;       uint2 o; o.x = cvtpk(xv[j].x * rs * g.x, xv[j].y * rs * g.y); o.y = cvtpk(xv[j].z * rs * g.z, xv[j].w * rs * g.w);
;       *(uint2*)(hin + base + j * 256 + lane * 4) = o;
;     }
	v_add_f32_e32 v35, v35, v54
	v_cndmask_b32_e32 v54, v200, v204, vcc
	v_lshlrev_b32_e32 v54, 2, v54
	ds_bpermute_b32 v54, v54, v35
	v_cmp_lt_i32_e32 vcc, v205, v202
	s_waitcnt lgkmcnt(0)
	v_add_f32_e32 v35, v35, v54
	v_cndmask_b32_e32 v54, v200, v205, vcc
	v_lshlrev_b32_e32 v54, 2, v54
	ds_bpermute_b32 v54, v54, v35
	v_cmp_lt_i32_e32 vcc, v206, v202
	s_waitcnt lgkmcnt(0)
	v_add_f32_e32 v35, v35, v54
	v_cndmask_b32_e32 v54, v200, v206, vcc
	v_lshlrev_b32_e32 v54, 2, v54
	ds_bpermute_b32 v54, v54, v35
	v_cmp_lt_i32_e32 vcc, v207, v202
	s_waitcnt lgkmcnt(0)
	v_add_f32_e32 v35, v35, v54
	v_cndmask_b32_e32 v54, v200, v207, vcc
	v_lshlrev_b32_e32 v54, 2, v54
	ds_bpermute_b32 v54, v54, v35
	v_cmp_lt_i32_e32 vcc, v208, v202
	s_waitcnt lgkmcnt(0)
	v_add_f32_e32 v35, v35, v54
	v_cndmask_b32_e32 v54, v200, v208, vcc
	v_lshlrev_b32_e32 v54, 2, v54
	ds_bpermute_b32 v54, v54, v35
	s_waitcnt lgkmcnt(0)
	v_add_f32_e32 v35, v35, v54
	v_fmamk_f32 v35, v35, 0x3a000000, v195
	v_cmp_gt_f32_e32 vcc, s38, v35
	v_mul_f32_e32 v54, 0x4b800000, v35
	s_nop 0
	v_cndmask_b32_e32 v35, v35, v54, vcc
	v_rsq_f32_e32 v35, v35
	s_nop 0
	v_mul_f32_e32 v54, 0x45800000, v35
	v_cndmask_b32_e32 v54, v35, v54, vcc
	v_pk_mul_f32 v[30:31], v[30:31], v[54:55] op_sel_hi:[1,0]
	v_pk_mul_f32 v[32:33], v[32:33], v[54:55] op_sel_hi:[1,0]
	s_waitcnt vmcnt(0)
	v_pk_mul_f32 v[30:31], v[62:63], v[30:31]
	v_pk_mul_f32 v[32:33], v[64:65], v[32:33]
	v_cvt_pk_bf16_f32 v30, v30, v31
	v_cvt_pk_bf16_f32 v31, v32, v33
	v_add_co_u32_e32 v32, vcc, s0, v66
	v_pk_mul_f32 v[26:27], v[26:27], v[54:55] op_sel_hi:[1,0]
	s_nop 0
	v_addc_co_u32_e32 v33, vcc, 0, v67, vcc
	flat_store_dwordx2 v[32:33], v[30:31]
	v_mov_b32_e32 v30, v178
	v_mov_b32_e32 v31, v179
	v_mov_b32_e32 v32, v180
	v_mov_b32_e32 v33, v181
	v_pk_mul_f32 v[28:29], v[28:29], v[54:55] op_sel_hi:[1,0]
	v_pk_mul_f32 v[22:23], v[22:23], v[54:55] op_sel_hi:[1,0]
	v_pk_mul_f32 v[24:25], v[24:25], v[54:55] op_sel_hi:[1,0]
	v_pk_mul_f32 v[18:19], v[18:19], v[54:55] op_sel_hi:[1,0]
	v_pk_mul_f32 v[20:21], v[20:21], v[54:55] op_sel_hi:[1,0]
	v_pk_mul_f32 v[14:15], v[14:15], v[54:55] op_sel_hi:[1,0]
	v_pk_mul_f32 v[16:17], v[16:17], v[54:55] op_sel_hi:[1,0]
	v_pk_mul_f32 v[10:11], v[10:11], v[54:55] op_sel_hi:[1,0]
	v_pk_mul_f32 v[12:13], v[12:13], v[54:55] op_sel_hi:[1,0]
	v_pk_mul_f32 v[6:7], v[6:7], v[54:55] op_sel_hi:[1,0]
	v_pk_mul_f32 v[8:9], v[8:9], v[54:55] op_sel_hi:[1,0]
	v_pk_mul_f32 v[2:3], v[2:3], v[54:55] op_sel_hi:[1,0]
	v_pk_mul_f32 v[4:5], v[4:5], v[54:55] op_sel_hi:[1,0]
	s_nop 0
	v_pk_mul_f32 v[26:27], v[30:31], v[26:27]
	v_pk_mul_f32 v[28:29], v[32:33], v[28:29]
	v_cvt_pk_bf16_f32 v26, v26, v27
	v_cvt_pk_bf16_f32 v27, v28, v29
	flat_store_dwordx2 v[56:57], v[26:27] offset:512
	v_mov_b32_e32 v26, v182
	v_mov_b32_e32 v27, v183
	v_mov_b32_e32 v28, v184
	v_mov_b32_e32 v29, v185
	s_nop 0
	v_pk_mul_f32 v[22:23], v[22:23], v[26:27]
	v_pk_mul_f32 v[24:25], v[24:25], v[28:29]
	v_cvt_pk_bf16_f32 v22, v22, v23
	v_cvt_pk_bf16_f32 v23, v24, v25
	flat_store_dwordx2 v[56:57], v[22:23] offset:1024
	v_mov_b32_e32 v22, v186
	v_mov_b32_e32 v23, v187
	v_mov_b32_e32 v24, v188
	v_mov_b32_e32 v25, v189
	s_nop 0
	v_pk_mul_f32 v[18:19], v[18:19], v[22:23]
	v_pk_mul_f32 v[20:21], v[20:21], v[24:25]
	v_cvt_pk_bf16_f32 v18, v18, v19
	v_cvt_pk_bf16_f32 v19, v20, v21
	flat_store_dwordx2 v[56:57], v[18:19] offset:1536
	v_mov_b32_e32 v18, v214
	v_mov_b32_e32 v19, v215
	v_mov_b32_e32 v20, v216
	v_mov_b32_e32 v21, v217
	s_nop 0
	v_pk_mul_f32 v[14:15], v[14:15], v[18:19]
	v_pk_mul_f32 v[16:17], v[16:17], v[20:21]
	v_cvt_pk_bf16_f32 v14, v14, v15
	v_cvt_pk_bf16_f32 v15, v16, v17
	flat_store_dwordx2 v[56:57], v[14:15] offset:2048
	v_mov_b32_e32 v14, v218
	v_mov_b32_e32 v15, v219
	v_mov_b32_e32 v16, v220
	v_mov_b32_e32 v17, v221
	s_nop 0
	v_pk_mul_f32 v[10:11], v[10:11], v[14:15]
	v_pk_mul_f32 v[12:13], v[12:13], v[16:17]
	v_cvt_pk_bf16_f32 v10, v10, v11
	v_cvt_pk_bf16_f32 v11, v12, v13
	flat_store_dwordx2 v[56:57], v[10:11] offset:2560
	v_mov_b32_e32 v10, v222
	v_mov_b32_e32 v11, v223
	v_mov_b32_e32 v12, v224
	v_mov_b32_e32 v13, v225
	s_nop 0
	v_pk_mul_f32 v[6:7], v[6:7], v[10:11]
	v_pk_mul_f32 v[8:9], v[8:9], v[12:13]
	v_cvt_pk_bf16_f32 v6, v6, v7
	v_cvt_pk_bf16_f32 v7, v8, v9
	flat_store_dwordx2 v[56:57], v[6:7] offset:3072
	v_mov_b32_e32 v6, v226
	v_mov_b32_e32 v7, v227
	v_mov_b32_e32 v8, v228
	v_mov_b32_e32 v9, v229
	s_nop 0
	v_pk_mul_f32 v[2:3], v[2:3], v[6:7]
	v_pk_mul_f32 v[4:5], v[4:5], v[8:9]
	v_cvt_pk_bf16_f32 v2, v2, v3
	v_cvt_pk_bf16_f32 v3, v4, v5
	flat_store_dwordx2 v[56:57], v[2:3] offset:3584

; DEV char* wsp(const Params& p) { char* w = p.ws; asm volatile("" : "+s"(w)); return w; }
; DEV void phase_prep(const Params& p, char* lds) {
;     ...
;     } else if (it < n_tr + n_rope + n_pec) {
;       int e = it - n_tr - n_rope; int l = e >> 5, kv = (e >> 4) & 1, c = e & 15;
;       const float* pe = (kv ? p.pe_v : p.pe_k) + (size_t)l * 4096;
;       const float* w1 = (kv ? p.c_v1 : p.c_k1) + (size_t)l * 4096 * 256;
;       float acc = 0.f;
;       for (int i = c * 256; i < c * 256 + 256; ++i) acc += pe[i] * w1[(size_t)i * 256 + tid];
;       ((float*)(wsp(p) + OFF_PEC))[((l * 2 + kv) * 16 + c) * 256 + tid] = acc;
.LBB0_1898:
	s_add_u32 s6, s3, s0
	s_addc_u32 s7, s4, s1
	global_load_dwordx4 v[6:9], v0, s[6:7] offset:48
	global_load_dwordx4 v[10:13], v0, s[6:7] offset:32
	global_load_dwordx4 v[14:17], v0, s[6:7] offset:16
	global_load_dwordx4 v[18:21], v0, s[6:7]
	s_movk_i32 s5, 0xd000
	v_add_co_u32_e32 v170, vcc, s5, v2
	s_nop 1
	v_addc_co_u32_e32 v171, vcc, -1, v3, vcc
	s_movk_i32 s5, 0xe000
	v_add_co_u32_e32 v172, vcc, s5, v2
	s_nop 1
	v_addc_co_u32_e32 v173, vcc, -1, v3, vcc
	s_movk_i32 s5, 0xf000
	v_add_co_u32_e32 v174, vcc, s5, v2
	s_nop 1
	v_addc_co_u32_e32 v175, vcc, -1, v3, vcc
	global_load_dword v152, v[170:171], off offset:-3072
	global_load_dword v153, v[170:171], off offset:-2048
	global_load_dword v154, v[170:171], off offset:-1024
	global_load_dword v155, v[172:173], off offset:-4096
	global_load_dword v156, v[172:173], off offset:-3072
	global_load_dword v157, v[172:173], off offset:-2048
	global_load_dword v158, v[172:173], off offset:-1024
	global_load_dword v159, v[172:173], off
	global_load_dword v160, v[174:175], off offset:-3072
	global_load_dword v161, v[174:175], off offset:-2048
	global_load_dword v162, v[174:175], off offset:-1024
	global_load_dword v163, v[2:3], off offset:-4096
	global_load_dword v164, v[2:3], off offset:-3072
	global_load_dword v165, v[2:3], off offset:-2048
	global_load_dword v166, v[2:3], off offset:-1024
	global_load_dword v167, v[2:3], off
	s_add_u32 s0, s0, 64
	s_addc_u32 s1, s1, 0
	s_mov_b64 s[6:7], 0x4000
	v_lshl_add_u64 v[2:3], v[2:3], 0, s[6:7]
	s_waitcnt vmcnt(0)
	v_fmac_f32_e32 v4, v18, v152
	v_fmac_f32_e32 v4, v19, v153
	v_fmac_f32_e32 v4, v20, v154
	v_fmac_f32_e32 v4, v21, v155
	v_fmac_f32_e32 v4, v14, v156
	v_fmac_f32_e32 v4, v15, v157
	v_fmac_f32_e32 v4, v16, v158
	v_fmac_f32_e32 v4, v17, v159
	v_fmac_f32_e32 v4, v10, v160
	v_fmac_f32_e32 v4, v11, v161
	v_fmac_f32_e32 v4, v12, v162
	v_fmac_f32_e32 v4, v13, v163
	v_fmac_f32_e32 v4, v6, v164
	v_fmac_f32_e32 v4, v7, v165
	v_fmac_f32_e32 v4, v8, v166
	v_fmac_f32_e32 v4, v9, v167
	s_cmpk_eq_i32 s0, 0x400
	s_cbranch_scc0 .LBB0_1898
	s_add_i32 s3, s20, 0xffff3380
	s_and_b32 s3, s3, 0xffffe0
	s_lshl_b32 s2, s2, 4
	s_and_b32 s4, s20, 15
	s_or_b32 s2, s2, s3
	s_or_b32 s2, s2, s4
	v_lshl_add_u32 v2, s2, 8, v34
	s_mov_b64 s[0:1], s[70:71]
	v_ashrrev_i32_e32 v3, 31, v2
	s_mov_b64 s[36:37], 0x1000
	v_lshl_add_u64 v[2:3], v[2:3], 2, s[0:1]
	v_add_co_u32_e32 v2, vcc, 0x19600000, v2
	s_mov_b32 s38, 0x800000
	s_nop 0
	v_addc_co_u32_e32 v3, vcc, 0, v3, vcc
	flat_store_dword v[2:3], v4
